# GEMM K-loops: LDS-DMA pieces rebalanced 2/6/2/6 to 4/4/4/4 per load segment (As[b][0] staged one segment later), vmcnt(6) in the B segments
# baseline (speedup 1.0000x reference)
; #define PG8_STAGE(bufoff, gbase, voff) do { _Pragma("unroll") for (int _i = 0; _i < 2; ++_i) \
;         __builtin_amdgcn_global_load_lds((const unsigned*)((const char*)(gbase) + (voff)[_i]), (PG8_LAS unsigned*)(lds + (bufoff) + ldsw + _i * 8192), 16, 0, 0); } while (0)
; #define PG8_WAIT_V(n) asm volatile("s_waitcnt vmcnt(" #n ")" ::: "memory")
; #define PG8_BAR __builtin_amdgcn_s_barrier()
; template <class Epi, class Sched, bool ALIGN_EPI = false, bool SP2 = false>
; __device__ __forceinline__ void gemm_phase(PG8_LAS unsigned char* lds, const Gemm g, const Sched& S, const Epi& E) {
;     ...
;     const unsigned ldsw = (unsigned)wid * 1024u;
;     const int aoff = lds_byte(wr * 64 + fr, fq * 8), boff = lds_byte(wc * 32 + fr, fq * 8);
;     ...
;         PG8_STAGE(PG8_SB(1, 0), cB + kstep, voffB); PG8_STAGE(PG8_SA(1, 0), cA + kstep, voffA); PG8_STAGE(PG8_SB(1, 1), cB + hstep + kstep, voffB);
;         PG8_WAIT_V(6); PG8_BAR;
.LBB0_125:
	s_add_u32 s60, s16, 0x1d200000
	s_addc_u32 s61, s17, 0
	s_add_u32 s6, s16, 0x18720000
	s_addc_u32 s7, s17, 0
	s_lshl_b32 s62, s10, 6
	s_lshl_b32 s35, s10, 13
	s_mov_b64 s[10:11], 0x80
	s_and_b32 s13, s34, 3
	s_add_i32 m0, s45, 0x18000
	v_lshl_add_u64 v[8:9], v[8:9], 0, s[10:11]
	s_lshl_b32 s38, s13, 5
	s_waitcnt vmcnt(2)
	s_barrier
	global_load_lds_dwordx4 v[8:9], off
	v_lshl_add_u64 v[6:7], v[6:7], 0, s[10:11]
	s_add_i32 m0, s45, 0x1a000
	s_add_i32 s63, s45, 0x8000
	s_add_i32 s70, s45, 0xa000
	global_load_lds_dwordx4 v[6:7], off
	v_mov_b32_e32 v240, v2
	v_mov_b32_e32 v241, v3
	v_lshl_add_u64 v[2:3], v[2:3], 0, s[10:11]
	s_mov_b32 m0, s63
	s_add_u32 s36, s46, 0x100080
	global_load_lds_dwordx4 v[2:3], off
	v_mov_b32_e32 v242, v4
	v_mov_b32_e32 v243, v5
	v_lshl_add_u64 v[2:3], v[4:5], 0, s[10:11]
	s_mov_b32 m0, s70
	s_addc_u32 s37, s47, 0
	global_load_lds_dwordx4 v[2:3], off
	s_add_i32 m0, s45, 0x1c000
	v_lshl_add_u64 v[2:3], s[36:37], 0, v[132:133]
	global_load_lds_dwordx4 v[2:3], off
	v_lshl_add_u64 v[2:3], s[36:37], 0, v[136:137]
	s_add_i32 m0, s45, 0x1e000
	v_bitop3_b32 v4, s38, 56, v163 bitop3:0xc8
	global_load_lds_dwordx4 v[2:3], off
	v_lshlrev_b32_e32 v138, 2, v4
	v_lshl_add_u64 v[6:7], s[16:17], 0, v[138:139]
	s_mov_b64 s[16:17], 0x18200000
	v_lshl_add_u64 v[140:141], v[6:7], 0, s[16:17]
	s_mov_b64 s[16:17], 0x18400000
	v_lshlrev_b32_e32 v5, 10, v1
	v_lshl_add_u64 v[142:143], v[6:7], 0, s[16:17]
	v_and_b32_e32 v5, 0xe0000, v5
	v_lshlrev_b32_e32 v6, 13, v161
	v_or3_b32 v5, v159, v5, v6
	v_lshlrev_b32_e32 v2, 6, v158
	s_movk_i32 s36, 0x3c0
	v_lshlrev_b32_e32 v3, 2, v158
	s_cmpk_lt_u32 s12, 0x100
	v_add_u32_e32 v144, v5, v160
	v_lshlrev_b32_e32 v5, 6, v162
	v_and_or_b32 v2, v2, s36, v164
	v_and_b32_e32 v3, 32, v3
	v_lshl_or_b32 v167, s13, 12, v165
	s_waitcnt vmcnt(6)
	s_cselect_b64 s[12:13], -1, 0
	s_lshl_b32 s34, s34, 6
	v_and_b32_e32 v5, 0x1e0000, v5
	v_bitop3_b32 v3, v2, s35, v3 bitop3:0xde
	v_or_b32_e32 v2, s38, v163
	s_and_b32 s34, s34, 0x80
	v_or3_b32 v5, v159, v5, v6
	s_add_i32 s74, 0, 0x10000
	s_add_i32 s75, 0, 0x14000
	v_or_b32_e32 v168, 16, v158
	v_or_b32_e32 v169, 32, v158
	v_or_b32_e32 v170, 48, v158
	s_ashr_i32 s71, s22, 31
	s_mov_b32 s72, s22
	v_mov_b32_e32 v145, v139
	v_add_u32_e32 v146, v5, v160
	v_mov_b32_e32 v147, v139
	s_movk_i32 s73, 0xa1
	v_add_u32_e32 v171, s74, v167
	v_add_u32_e32 v172, s75, v167
	v_add_u32_e32 v173, 0, v3
	s_lshl_b32 s76, s34, 1
	v_lshlrev_b32_e32 v138, 1, v2
	v_lshlrev_b32_e32 v148, 1, v4
	s_movk_i32 s77, 0xfcf
	s_movk_i32 s78, 0xfef
	v_mov_b64_e32 v[150:151], 0x4ff
	v_mov_b32_e32 v174, 0xfdf
	v_mov_b32_e32 v175, 0xfff
	s_barrier
	s_branch .LBB0_128

; #define PG8_STAGE(bufoff, gbase, voff) do { _Pragma("unroll") for (int _i = 0; _i < 2; ++_i) \
;         __builtin_amdgcn_global_load_lds((const unsigned*)((const char*)(gbase) + (voff)[_i]), (PG8_LAS unsigned*)(lds + (bufoff) + ldsw + _i * 8192), 16, 0, 0); } while (0)
; #define PG8_LDA(dst, b, h) do { _Pragma("unroll") for (int m = 0; m < 4; ++m) _Pragma("unroll") for (int k = 0; k < 2; ++k) dst[m][k] = *(const PG8_LAS bf16x8*)(lds + PG8_SA(b, h) + aoff + m * 2048 + k * 1024); } while (0)
; #define PG8_LDB(dst, b, h) do { _Pragma("unroll") for (int n = 0; n < 2; ++n) _Pragma("unroll") for (int k = 0; k < 2; ++k) dst[n][k] = *(const PG8_LAS bf16x8*)(lds + PG8_SB(b, h) + boff + n * 2048 + k * 1024); } while (0)
; #define PG8_MMA(ai, bj, At, Bt) do { __builtin_amdgcn_s_setprio(1); _Pragma("unroll") for (int m = 0; m < 4; ++m) _Pragma("unroll") for (int n = 0; n < 2; ++n) _Pragma("unroll") for (int k = 0; k < 2; ++k) \
;         acc[ai][bj][m][n] = __builtin_amdgcn_mfma_f32_16x16x32_bf16(Bt[n][k], At[m][k], acc[ai][bj][m][n], 0, 0, 0); __builtin_amdgcn_s_setprio(0); } while (0)
; #define PG8_WAIT_V(n) asm volatile("s_waitcnt vmcnt(" #n ")" ::: "memory")
; #define PG8_WAIT_L(n) asm volatile("s_waitcnt lgkmcnt(" #n ")" ::: "memory")
; #define PG8_BAR __builtin_amdgcn_s_barrier()
; #define PG8_SCHED __builtin_amdgcn_sched_barrier(0)
; template <class Epi, class Sched, bool ALIGN_EPI = false, bool SP2 = false>
; __device__ __forceinline__ void gemm_phase(PG8_LAS unsigned char* lds, const Gemm g, const Sched& S, const Epi& E) {
;     ...
;             PG8_LDB(B0, 0, 0); PG8_LDB(B1, 0, 1); PG8_SCHED; PG8_LDA(At, 0, 0); PG8_STAGE(PG8_SA(1, 1), a1 + hstep, voffA);
;             PG8_WAIT_V(8); PG8_WAIT_L(0); PG8_BAR; PG8_MMA(0, 0, At, B0); PG8_MMA(0, 1, At, B1); PG8_BAR; PG8_SCHED;
;             PG8_LDA(At, 0, 1); PG8_STAGE(PG8_SB(0, 0), b2, voffB); PG8_STAGE(PG8_SB(0, 1), b2 + hstep, voffB); PG8_STAGE(PG8_SA(0, 0), a2, voffA);
.LBB0_132:
	ds_read_b128 v[152:155], v171
	ds_read_b128 v[176:179], v171 offset:1024
	ds_read_b128 v[180:183], v171 offset:2048
	ds_read_b128 v[184:187], v171 offset:3072
	ds_read_b128 v[188:191], v172
	ds_read_b128 v[192:195], v172 offset:1024
	ds_read_b128 v[198:201], v172 offset:2048
	ds_read_b128 v[202:205], v172 offset:3072
	s_add_u32 s46, s2, 0xfff00080
	s_addc_u32 s47, s3, -1
	s_cmp_eq_u32 s82, 60
	s_cselect_b32 s49, s35, s47
	s_cselect_b32 s48, s43, s46
	s_cselect_b32 s47, s17, s81
	s_cselect_b32 s46, s79, s80
	v_lshl_add_u64 v[156:157], v[240:241], 0, s[10:11]
	s_mov_b32 m0, s63
	s_nop 0
	global_load_lds_dwordx4 v[156:157], off
	v_lshl_add_u64 v[156:157], v[242:243], 0, s[10:11]
	s_mov_b32 m0, s70
	s_nop 0
	global_load_lds_dwordx4 v[156:157], off
	v_lshl_add_u64 v[156:157], s[2:3], 0, v[144:145]
	s_add_i32 m0, s45, 0xc000
	ds_read_b128 v[206:209], v173
	ds_read_b128 v[210:213], v173 offset:1024
	ds_read_b128 v[214:217], v173 offset:2048
	ds_read_b128 v[218:221], v173 offset:3072
	ds_read_b128 v[222:225], v173 offset:4096
	ds_read_b128 v[226:229], v173 offset:5120
	ds_read_b128 v[230:233], v173 offset:6144
	ds_read_b128 v[234:237], v173 offset:7168
	global_load_lds_dwordx4 v[156:157], off
	v_lshl_add_u64 v[156:157], s[2:3], 0, v[146:147]
	s_add_i32 m0, s45, 0xe000
	s_nop 0
	global_load_lds_dwordx4 v[156:157], off
	s_waitcnt vmcnt(8)
	s_waitcnt lgkmcnt(0)
	s_barrier
	s_setprio 1
	s_waitcnt lgkmcnt(0)
	v_mfma_f32_16x16x32_bf16 v[126:129], v[152:155], v[206:209], v[126:129]
	v_mfma_f32_16x16x32_bf16 v[122:125], v[180:183], v[206:209], v[122:125]
	v_mfma_f32_16x16x32_bf16 v[110:113], v[152:155], v[214:217], v[110:113]
	v_mfma_f32_16x16x32_bf16 v[106:109], v[180:183], v[214:217], v[106:109]
	v_mfma_f32_16x16x32_bf16 v[94:97], v[152:155], v[222:225], v[94:97]
	v_mfma_f32_16x16x32_bf16 v[90:93], v[180:183], v[222:225], v[90:93]
	v_mfma_f32_16x16x32_bf16 v[78:81], v[152:155], v[230:233], v[78:81]
	v_mfma_f32_16x16x32_bf16 v[74:77], v[180:183], v[230:233], v[74:77]
	v_mfma_f32_16x16x32_bf16 v[126:129], v[176:179], v[210:213], v[126:129]
	v_mfma_f32_16x16x32_bf16 v[122:125], v[184:187], v[210:213], v[122:125]
	v_mfma_f32_16x16x32_bf16 v[110:113], v[176:179], v[218:221], v[110:113]
	v_mfma_f32_16x16x32_bf16 v[106:109], v[184:187], v[218:221], v[106:109]
	v_mfma_f32_16x16x32_bf16 v[94:97], v[176:179], v[226:229], v[94:97]
	v_mfma_f32_16x16x32_bf16 v[90:93], v[184:187], v[226:229], v[90:93]
	v_mfma_f32_16x16x32_bf16 v[78:81], v[176:179], v[234:237], v[78:81]
	v_mfma_f32_16x16x32_bf16 v[74:77], v[184:187], v[234:237], v[74:77]
	s_setprio 0
	s_setprio 1
	v_mfma_f32_16x16x32_bf16 v[118:121], v[188:191], v[206:209], v[118:121]
	v_mfma_f32_16x16x32_bf16 v[114:117], v[198:201], v[206:209], v[114:117]
	v_mfma_f32_16x16x32_bf16 v[102:105], v[188:191], v[214:217], v[102:105]
	v_mfma_f32_16x16x32_bf16 v[98:101], v[198:201], v[214:217], v[98:101]
	v_mfma_f32_16x16x32_bf16 v[86:89], v[188:191], v[222:225], v[86:89]
	v_mfma_f32_16x16x32_bf16 v[82:85], v[198:201], v[222:225], v[82:85]
	v_mfma_f32_16x16x32_bf16 v[70:73], v[188:191], v[230:233], v[70:73]
	v_mfma_f32_16x16x32_bf16 v[66:69], v[198:201], v[230:233], v[66:69]
	v_mfma_f32_16x16x32_bf16 v[118:121], v[192:195], v[210:213], v[118:121]
	v_mfma_f32_16x16x32_bf16 v[114:117], v[202:205], v[210:213], v[114:117]
	v_mfma_f32_16x16x32_bf16 v[102:105], v[192:195], v[218:221], v[102:105]
	v_mfma_f32_16x16x32_bf16 v[98:101], v[202:205], v[218:221], v[98:101]
	v_mfma_f32_16x16x32_bf16 v[86:89], v[192:195], v[226:229], v[86:89]
	v_mfma_f32_16x16x32_bf16 v[82:85], v[202:205], v[226:229], v[82:85]
	v_mfma_f32_16x16x32_bf16 v[70:73], v[192:195], v[234:237], v[70:73]
	v_mfma_f32_16x16x32_bf16 v[66:69], v[202:205], v[234:237], v[66:69]
	s_setprio 0
	s_barrier
	s_add_i32 s83, s74, s55
	v_lshl_add_u64 v[156:157], s[46:47], 0, v[132:133]
	s_mov_b32 m0, s83
	ds_read_b128 v[206:209], v173 offset:16384
	ds_read_b128 v[210:213], v173 offset:17408
	ds_read_b128 v[214:217], v173 offset:18432
	ds_read_b128 v[218:221], v173 offset:19456
	ds_read_b128 v[222:225], v173 offset:20480
	ds_read_b128 v[226:229], v173 offset:21504
	ds_read_b128 v[230:233], v173 offset:22528
	ds_read_b128 v[234:237], v173 offset:23552
	global_load_lds_dwordx4 v[156:157], off
	s_add_i32 m0, s83, 0x2000
	s_add_u32 s84, s46, 0x100000
	v_lshl_add_u64 v[238:239], s[46:47], 0, v[136:137]
	s_addc_u32 s85, s47, 0
	s_add_i32 s83, s75, s55
	global_load_lds_dwordx4 v[238:239], off
	v_lshl_add_u64 v[240:241], s[84:85], 0, v[132:133]
	s_mov_b32 m0, s83
	v_lshl_add_u64 v[242:243], s[48:49], 0, v[134:135]
	global_load_lds_dwordx4 v[240:241], off
	v_lshl_add_u64 v[240:241], s[84:85], 0, v[136:137]
	s_add_i32 m0, s83, 0x2000
	s_nop 0
	global_load_lds_dwordx4 v[240:241], off
	v_lshl_add_u64 v[240:241], s[48:49], 0, v[130:131]
	s_waitcnt vmcnt(6)
	s_waitcnt lgkmcnt(0)
	s_barrier
; #define PG8_STAGE(bufoff, gbase, voff) do { _Pragma("unroll") for (int _i = 0; _i < 2; ++_i) \
;         __builtin_amdgcn_global_load_lds((const unsigned*)((const char*)(gbase) + (voff)[_i]), (PG8_LAS unsigned*)(lds + (bufoff) + ldsw + _i * 8192), 16, 0, 0); } while (0)
; #define PG8_LDA(dst, b, h) do { _Pragma("unroll") for (int m = 0; m < 4; ++m) _Pragma("unroll") for (int k = 0; k < 2; ++k) dst[m][k] = *(const PG8_LAS bf16x8*)(lds + PG8_SA(b, h) + aoff + m * 2048 + k * 1024); } while (0)
; #define PG8_LDB(dst, b, h) do { _Pragma("unroll") for (int n = 0; n < 2; ++n) _Pragma("unroll") for (int k = 0; k < 2; ++k) dst[n][k] = *(const PG8_LAS bf16x8*)(lds + PG8_SB(b, h) + boff + n * 2048 + k * 1024); } while (0)
; #define PG8_MMA(ai, bj, At, Bt) do { __builtin_amdgcn_s_setprio(1); _Pragma("unroll") for (int m = 0; m < 4; ++m) _Pragma("unroll") for (int n = 0; n < 2; ++n) _Pragma("unroll") for (int k = 0; k < 2; ++k) \
;         acc[ai][bj][m][n] = __builtin_amdgcn_mfma_f32_16x16x32_bf16(Bt[n][k], At[m][k], acc[ai][bj][m][n], 0, 0, 0); __builtin_amdgcn_s_setprio(0); } while (0)
; #define PG8_WAIT_V(n) asm volatile("s_waitcnt vmcnt(" #n ")" ::: "memory")
; #define PG8_WAIT_L(n) asm volatile("s_waitcnt lgkmcnt(" #n ")" ::: "memory")
; #define PG8_BAR __builtin_amdgcn_s_barrier()
; #define PG8_SCHED __builtin_amdgcn_sched_barrier(0)
; template <class Epi, class Sched, bool ALIGN_EPI = false, bool SP2 = false>
; __device__ __forceinline__ void gemm_phase(PG8_LAS unsigned char* lds, const Gemm g, const Sched& S, const Epi& E) {
;     ...
;             PG8_LDA(At, 0, 1); PG8_STAGE(PG8_SB(0, 0), b2, voffB); PG8_STAGE(PG8_SB(0, 1), b2 + hstep, voffB); PG8_STAGE(PG8_SA(0, 0), a2, voffA);
;             PG8_WAIT_V(8); PG8_WAIT_L(0); PG8_BAR; PG8_MMA(1, 0, At, B0); PG8_MMA(1, 1, At, B1); PG8_BAR; PG8_SCHED;
;             PG8_LDB(B0, 1, 0); PG8_LDB(B1, 1, 1); PG8_SCHED; PG8_LDA(At, 1, 0); PG8_STAGE(PG8_SA(0, 1), a2 + hstep, voffA);
	s_setprio 1
	s_waitcnt lgkmcnt(0)
	v_mfma_f32_16x16x32_bf16 v[62:65], v[152:155], v[206:209], v[62:65]
	v_mfma_f32_16x16x32_bf16 v[58:61], v[180:183], v[206:209], v[58:61]
	v_mfma_f32_16x16x32_bf16 v[46:49], v[152:155], v[214:217], v[46:49]
	v_mfma_f32_16x16x32_bf16 v[42:45], v[180:183], v[214:217], v[42:45]
	v_mfma_f32_16x16x32_bf16 v[30:33], v[152:155], v[222:225], v[30:33]
	v_mfma_f32_16x16x32_bf16 v[26:29], v[180:183], v[222:225], v[26:29]
	v_mfma_f32_16x16x32_bf16 v[14:17], v[152:155], v[230:233], v[14:17]
	v_mfma_f32_16x16x32_bf16 v[10:13], v[180:183], v[230:233], v[10:13]
	v_mfma_f32_16x16x32_bf16 v[62:65], v[176:179], v[210:213], v[62:65]
	v_mfma_f32_16x16x32_bf16 v[58:61], v[184:187], v[210:213], v[58:61]
	v_mfma_f32_16x16x32_bf16 v[46:49], v[176:179], v[218:221], v[46:49]
	v_mfma_f32_16x16x32_bf16 v[42:45], v[184:187], v[218:221], v[42:45]
	v_mfma_f32_16x16x32_bf16 v[30:33], v[176:179], v[226:229], v[30:33]
	v_mfma_f32_16x16x32_bf16 v[26:29], v[184:187], v[226:229], v[26:29]
	v_mfma_f32_16x16x32_bf16 v[14:17], v[176:179], v[234:237], v[14:17]
	v_mfma_f32_16x16x32_bf16 v[10:13], v[184:187], v[234:237], v[10:13]
	s_setprio 0
	s_setprio 1
	v_mfma_f32_16x16x32_bf16 v[54:57], v[188:191], v[206:209], v[54:57]
	v_mfma_f32_16x16x32_bf16 v[50:53], v[198:201], v[206:209], v[50:53]
	v_mfma_f32_16x16x32_bf16 v[38:41], v[188:191], v[214:217], v[38:41]
	v_mfma_f32_16x16x32_bf16 v[34:37], v[198:201], v[214:217], v[34:37]
	v_mfma_f32_16x16x32_bf16 v[22:25], v[188:191], v[222:225], v[22:25]
	v_mfma_f32_16x16x32_bf16 v[18:21], v[198:201], v[222:225], v[18:21]
	v_mfma_f32_16x16x32_bf16 v[6:9], v[188:191], v[230:233], v[6:9]
	v_mfma_f32_16x16x32_bf16 v[2:5], v[198:201], v[230:233], v[2:5]
	v_mfma_f32_16x16x32_bf16 v[54:57], v[192:195], v[210:213], v[54:57]
	v_mfma_f32_16x16x32_bf16 v[50:53], v[202:205], v[210:213], v[50:53]
	v_mfma_f32_16x16x32_bf16 v[38:41], v[192:195], v[218:221], v[38:41]
	v_mfma_f32_16x16x32_bf16 v[34:37], v[202:205], v[218:221], v[34:37]
	v_mfma_f32_16x16x32_bf16 v[22:25], v[192:195], v[226:229], v[22:25]
	v_mfma_f32_16x16x32_bf16 v[18:21], v[202:205], v[226:229], v[18:21]
	v_mfma_f32_16x16x32_bf16 v[6:9], v[192:195], v[234:237], v[6:9]
	v_mfma_f32_16x16x32_bf16 v[2:5], v[202:205], v[234:237], v[2:5]
	s_setprio 0
	s_barrier
	s_add_i32 s83, 0, 0x18000
	v_add_u32_e32 v149, s83, v167
	s_add_i32 s84, 0, 0x1c000
	ds_read_b128 v[152:155], v149
	ds_read_b128 v[176:179], v149 offset:1024
	ds_read_b128 v[180:183], v149 offset:2048
	ds_read_b128 v[184:187], v149 offset:3072
	v_add_u32_e32 v149, s84, v167
	ds_read_b128 v[188:191], v149
	ds_read_b128 v[192:195], v149 offset:1024
	ds_read_b128 v[198:201], v149 offset:2048
	ds_read_b128 v[202:205], v149 offset:3072
	s_add_u32 s48, s48, 0x100000
	s_addc_u32 s49, s49, 0
	s_mov_b32 m0, s45
	s_nop 0
	global_load_lds_dwordx4 v[240:241], off
	s_mov_b32 m0, s56
	s_nop 0
	global_load_lds_dwordx4 v[242:243], off
	s_mov_b32 m0, s57
	v_lshl_add_u64 v[244:245], s[48:49], 0, v[130:131]
	ds_read_b128 v[206:209], v173 offset:32768
	ds_read_b128 v[210:213], v173 offset:33792
	ds_read_b128 v[214:217], v173 offset:34816
	ds_read_b128 v[218:221], v173 offset:35840
	ds_read_b128 v[222:225], v173 offset:36864
	ds_read_b128 v[226:229], v173 offset:37888
	ds_read_b128 v[230:233], v173 offset:38912
	ds_read_b128 v[234:237], v173 offset:39936
	global_load_lds_dwordx4 v[244:245], off
	v_lshl_add_u64 v[244:245], s[48:49], 0, v[134:135]
	s_mov_b32 m0, s58
	s_nop 0
	global_load_lds_dwordx4 v[244:245], off
	s_waitcnt vmcnt(8)
	s_waitcnt lgkmcnt(0)
	s_barrier
; #define PG8_STAGE(bufoff, gbase, voff) do { _Pragma("unroll") for (int _i = 0; _i < 2; ++_i) \
;         __builtin_amdgcn_global_load_lds((const unsigned*)((const char*)(gbase) + (voff)[_i]), (PG8_LAS unsigned*)(lds + (bufoff) + ldsw + _i * 8192), 16, 0, 0); } while (0)
; #define PG8_LDA(dst, b, h) do { _Pragma("unroll") for (int m = 0; m < 4; ++m) _Pragma("unroll") for (int k = 0; k < 2; ++k) dst[m][k] = *(const PG8_LAS bf16x8*)(lds + PG8_SA(b, h) + aoff + m * 2048 + k * 1024); } while (0)
; #define PG8_LDB(dst, b, h) do { _Pragma("unroll") for (int n = 0; n < 2; ++n) _Pragma("unroll") for (int k = 0; k < 2; ++k) dst[n][k] = *(const PG8_LAS bf16x8*)(lds + PG8_SB(b, h) + boff + n * 2048 + k * 1024); } while (0)
; #define PG8_MMA(ai, bj, At, Bt) do { __builtin_amdgcn_s_setprio(1); _Pragma("unroll") for (int m = 0; m < 4; ++m) _Pragma("unroll") for (int n = 0; n < 2; ++n) _Pragma("unroll") for (int k = 0; k < 2; ++k) \
;         acc[ai][bj][m][n] = __builtin_amdgcn_mfma_f32_16x16x32_bf16(Bt[n][k], At[m][k], acc[ai][bj][m][n], 0, 0, 0); __builtin_amdgcn_s_setprio(0); } while (0)
; #define PG8_WAIT_V(n) asm volatile("s_waitcnt vmcnt(" #n ")" ::: "memory")
; #define PG8_WAIT_L(n) asm volatile("s_waitcnt lgkmcnt(" #n ")" ::: "memory")
; #define PG8_BAR __builtin_amdgcn_s_barrier()
; #define PG8_SCHED __builtin_amdgcn_sched_barrier(0)
; template <class Epi, class Sched, bool ALIGN_EPI = false, bool SP2 = false>
; __device__ __forceinline__ void gemm_phase(PG8_LAS unsigned char* lds, const Gemm g, const Sched& S, const Epi& E) {
;     ...
;             PG8_LDB(B0, 1, 0); PG8_LDB(B1, 1, 1); PG8_SCHED; PG8_LDA(At, 1, 0); PG8_STAGE(PG8_SA(0, 1), a2 + hstep, voffA);
;             PG8_WAIT_V(8); PG8_WAIT_L(0); PG8_BAR; PG8_MMA(0, 0, At, B0); PG8_MMA(0, 1, At, B1); PG8_BAR; PG8_SCHED;
;             PG8_LDA(At, 1, 1); PG8_STAGE(PG8_SB(1, 0), b3, voffB); PG8_STAGE(PG8_SB(1, 1), b3 + hstep, voffB); PG8_STAGE(PG8_SA(1, 0), a3, voffA);
;             PG8_WAIT_V(8); PG8_WAIT_L(0); PG8_BAR; PG8_MMA(1, 0, At, B0); PG8_MMA(1, 1, At, B1); PG8_BAR; PG8_SCHED;
	s_setprio 1
	s_waitcnt lgkmcnt(0)
	v_mfma_f32_16x16x32_bf16 v[126:129], v[152:155], v[206:209], v[126:129]
	v_mfma_f32_16x16x32_bf16 v[122:125], v[180:183], v[206:209], v[122:125]
	v_mfma_f32_16x16x32_bf16 v[110:113], v[152:155], v[214:217], v[110:113]
	v_mfma_f32_16x16x32_bf16 v[106:109], v[180:183], v[214:217], v[106:109]
	v_mfma_f32_16x16x32_bf16 v[94:97], v[152:155], v[222:225], v[94:97]
	v_mfma_f32_16x16x32_bf16 v[90:93], v[180:183], v[222:225], v[90:93]
	v_mfma_f32_16x16x32_bf16 v[78:81], v[152:155], v[230:233], v[78:81]
	v_mfma_f32_16x16x32_bf16 v[74:77], v[180:183], v[230:233], v[74:77]
	v_mfma_f32_16x16x32_bf16 v[126:129], v[176:179], v[210:213], v[126:129]
	v_mfma_f32_16x16x32_bf16 v[122:125], v[184:187], v[210:213], v[122:125]
	v_mfma_f32_16x16x32_bf16 v[110:113], v[176:179], v[218:221], v[110:113]
	v_mfma_f32_16x16x32_bf16 v[106:109], v[184:187], v[218:221], v[106:109]
	v_mfma_f32_16x16x32_bf16 v[94:97], v[176:179], v[226:229], v[94:97]
	v_mfma_f32_16x16x32_bf16 v[90:93], v[184:187], v[226:229], v[90:93]
	v_mfma_f32_16x16x32_bf16 v[78:81], v[176:179], v[234:237], v[78:81]
	v_mfma_f32_16x16x32_bf16 v[74:77], v[184:187], v[234:237], v[74:77]
	s_setprio 0
	s_setprio 1
	v_mfma_f32_16x16x32_bf16 v[118:121], v[188:191], v[206:209], v[118:121]
	v_mfma_f32_16x16x32_bf16 v[114:117], v[198:201], v[206:209], v[114:117]
	v_mfma_f32_16x16x32_bf16 v[102:105], v[188:191], v[214:217], v[102:105]
	v_mfma_f32_16x16x32_bf16 v[98:101], v[198:201], v[214:217], v[98:101]
	v_mfma_f32_16x16x32_bf16 v[86:89], v[188:191], v[222:225], v[86:89]
	v_mfma_f32_16x16x32_bf16 v[82:85], v[198:201], v[222:225], v[82:85]
	v_mfma_f32_16x16x32_bf16 v[70:73], v[188:191], v[230:233], v[70:73]
	v_mfma_f32_16x16x32_bf16 v[66:69], v[198:201], v[230:233], v[66:69]
	v_mfma_f32_16x16x32_bf16 v[118:121], v[192:195], v[210:213], v[118:121]
	v_mfma_f32_16x16x32_bf16 v[114:117], v[202:205], v[210:213], v[114:117]
	v_mfma_f32_16x16x32_bf16 v[102:105], v[192:195], v[218:221], v[102:105]
	v_mfma_f32_16x16x32_bf16 v[98:101], v[202:205], v[218:221], v[98:101]
	v_mfma_f32_16x16x32_bf16 v[86:89], v[192:195], v[226:229], v[86:89]
	v_mfma_f32_16x16x32_bf16 v[82:85], v[202:205], v[226:229], v[82:85]
	v_mfma_f32_16x16x32_bf16 v[70:73], v[192:195], v[234:237], v[70:73]
	v_mfma_f32_16x16x32_bf16 v[66:69], v[202:205], v[234:237], v[66:69]
	s_setprio 0
	s_barrier
	s_add_i32 s48, s83, s55
	v_lshl_add_u64 v[156:157], v[156:157], 0, s[10:11]
	s_mov_b32 m0, s48
	ds_read_b128 v[206:209], v173 offset:49152
	ds_read_b128 v[210:213], v173 offset:50176
	ds_read_b128 v[214:217], v173 offset:51200
	ds_read_b128 v[218:221], v173 offset:52224
	ds_read_b128 v[222:225], v173 offset:53248
	ds_read_b128 v[226:229], v173 offset:54272
	ds_read_b128 v[230:233], v173 offset:55296
	ds_read_b128 v[234:237], v173 offset:56320
	global_load_lds_dwordx4 v[156:157], off
	s_add_i32 m0, s48, 0x2000
	s_add_u32 s46, s46, 0x100080
	v_lshl_add_u64 v[156:157], v[238:239], 0, s[10:11]
	s_addc_u32 s47, s47, 0
	s_add_i32 s48, s84, s55
	global_load_lds_dwordx4 v[156:157], off
	v_lshl_add_u64 v[156:157], s[46:47], 0, v[132:133]
	s_mov_b32 m0, s48
	s_nop 0
	global_load_lds_dwordx4 v[156:157], off
	v_lshl_add_u64 v[156:157], s[46:47], 0, v[136:137]
	s_add_i32 m0, s48, 0x2000
	s_nop 0
	global_load_lds_dwordx4 v[156:157], off
	s_waitcnt vmcnt(6)
	s_waitcnt lgkmcnt(0)
	s_barrier
	s_setprio 1
	s_waitcnt lgkmcnt(0)
	v_mfma_f32_16x16x32_bf16 v[62:65], v[152:155], v[206:209], v[62:65]
	v_mfma_f32_16x16x32_bf16 v[58:61], v[180:183], v[206:209], v[58:61]
	v_mfma_f32_16x16x32_bf16 v[46:49], v[152:155], v[214:217], v[46:49]
	v_mfma_f32_16x16x32_bf16 v[42:45], v[180:183], v[214:217], v[42:45]
	v_mfma_f32_16x16x32_bf16 v[30:33], v[152:155], v[222:225], v[30:33]
	v_mfma_f32_16x16x32_bf16 v[26:29], v[180:183], v[222:225], v[26:29]
	v_mfma_f32_16x16x32_bf16 v[14:17], v[152:155], v[230:233], v[14:17]
	v_mfma_f32_16x16x32_bf16 v[10:13], v[180:183], v[230:233], v[10:13]
	v_mfma_f32_16x16x32_bf16 v[62:65], v[176:179], v[210:213], v[62:65]
	v_mfma_f32_16x16x32_bf16 v[58:61], v[184:187], v[210:213], v[58:61]
	v_mfma_f32_16x16x32_bf16 v[46:49], v[176:179], v[218:221], v[46:49]
	v_mfma_f32_16x16x32_bf16 v[42:45], v[184:187], v[218:221], v[42:45]
	v_mfma_f32_16x16x32_bf16 v[30:33], v[176:179], v[226:229], v[30:33]
	v_mfma_f32_16x16x32_bf16 v[26:29], v[184:187], v[226:229], v[26:29]
	v_mfma_f32_16x16x32_bf16 v[14:17], v[176:179], v[234:237], v[14:17]
	v_mfma_f32_16x16x32_bf16 v[10:13], v[184:187], v[234:237], v[10:13]
	s_setprio 0
	s_setprio 1
	v_mfma_f32_16x16x32_bf16 v[54:57], v[188:191], v[206:209], v[54:57]
	v_mfma_f32_16x16x32_bf16 v[50:53], v[198:201], v[206:209], v[50:53]
	v_mfma_f32_16x16x32_bf16 v[38:41], v[188:191], v[214:217], v[38:41]
	v_mfma_f32_16x16x32_bf16 v[34:37], v[198:201], v[214:217], v[34:37]
	v_mfma_f32_16x16x32_bf16 v[22:25], v[188:191], v[222:225], v[22:25]
	v_mfma_f32_16x16x32_bf16 v[18:21], v[198:201], v[222:225], v[18:21]
	v_mfma_f32_16x16x32_bf16 v[6:9], v[188:191], v[230:233], v[6:9]
	v_mfma_f32_16x16x32_bf16 v[2:5], v[198:201], v[230:233], v[2:5]
	v_mfma_f32_16x16x32_bf16 v[54:57], v[192:195], v[210:213], v[54:57]
	v_mfma_f32_16x16x32_bf16 v[50:53], v[202:205], v[210:213], v[50:53]
	v_mfma_f32_16x16x32_bf16 v[38:41], v[192:195], v[218:221], v[38:41]
	v_mfma_f32_16x16x32_bf16 v[34:37], v[202:205], v[218:221], v[34:37]
	v_mfma_f32_16x16x32_bf16 v[22:25], v[192:195], v[226:229], v[22:25]
	v_mfma_f32_16x16x32_bf16 v[18:21], v[202:205], v[226:229], v[18:21]
	v_mfma_f32_16x16x32_bf16 v[6:9], v[192:195], v[234:237], v[6:9]
	v_mfma_f32_16x16x32_bf16 v[2:5], v[202:205], v[234:237], v[2:5]
	s_setprio 0
	s_barrier
	s_add_i32 s82, s82, 2
	s_add_u32 s2, s2, 0x100
	s_addc_u32 s3, s3, 0
	s_add_u32 s80, s80, 0x100
	s_addc_u32 s81, s81, 0
	s_cmp_gt_u32 s82, 61
	s_cbranch_scc0 .LBB0_132
	s_and_b64 vcc, exec, s[12:13]
	s_cbranch_vccz .LBB0_135
	s_barrier

; #define PG8_STAGE(bufoff, gbase, voff) do { _Pragma("unroll") for (int _i = 0; _i < 2; ++_i) \
;         __builtin_amdgcn_global_load_lds((const unsigned*)((const char*)(gbase) + (voff)[_i]), (PG8_LAS unsigned*)(lds + (bufoff) + ldsw + _i * 8192), 16, 0, 0); } while (0)
; #define PG8_WAIT_V(n) asm volatile("s_waitcnt vmcnt(" #n ")" ::: "memory")
; #define PG8_BAR __builtin_amdgcn_s_barrier()
; template <class Epi, class Sched, bool ALIGN_EPI = false, bool SP2 = false>
; __device__ __forceinline__ void gemm_phase(PG8_LAS unsigned char* lds, const Gemm g, const Sched& S, const Epi& E) {
;     ...
;     const unsigned ldsw = (unsigned)wid * 1024u;
;     const int aoff = lds_byte(wr * 64 + fr, fq * 8), boff = lds_byte(wc * 32 + fr, fq * 8);
;     ...
;         PG8_STAGE(PG8_SB(1, 0), cB + kstep, voffB); PG8_STAGE(PG8_SA(1, 0), cA + kstep, voffA); PG8_STAGE(PG8_SB(1, 1), cB + hstep + kstep, voffB);
;         PG8_WAIT_V(6); PG8_BAR;
.LBB0_210:
	s_add_u32 s61, s16, 0x1d200000
	s_addc_u32 s62, s17, 0
	s_add_u32 s6, s16, 0x18720000
	s_addc_u32 s7, s17, 0
	s_lshl_b32 s63, s10, 6
	s_lshl_b32 s13, s10, 13
	s_mov_b64 s[10:11], 0x80
	s_and_b32 s3, s34, 3
	s_add_i32 m0, s56, 0x18000
	v_lshl_add_u64 v[8:9], v[8:9], 0, s[10:11]
	s_lshl_b32 s35, s3, 5
	s_waitcnt vmcnt(2)
	s_barrier
	global_load_lds_dwordx4 v[8:9], off
	v_lshl_add_u64 v[6:7], v[6:7], 0, s[10:11]
	s_add_i32 m0, s56, 0x1a000
	s_add_i32 s70, s56, 0x8000
	s_add_i32 s71, s56, 0xa000
	global_load_lds_dwordx4 v[6:7], off
	v_mov_b32_e32 v232, v2
	v_mov_b32_e32 v233, v3
	v_lshl_add_u64 v[2:3], v[2:3], 0, s[10:11]
	s_mov_b32 m0, s70
	s_add_u32 s36, s46, 0x100080
	global_load_lds_dwordx4 v[2:3], off
	v_mov_b32_e32 v234, v4
	v_mov_b32_e32 v235, v5
	v_lshl_add_u64 v[2:3], v[4:5], 0, s[10:11]
	s_mov_b32 m0, s71
	s_addc_u32 s37, s47, 0
	global_load_lds_dwordx4 v[2:3], off
	s_add_i32 m0, s56, 0x1c000
	v_lshl_add_u64 v[2:3], s[36:37], 0, v[132:133]
	global_load_lds_dwordx4 v[2:3], off
	v_lshl_add_u64 v[2:3], s[36:37], 0, v[136:137]
	s_add_i32 m0, s56, 0x1e000
	v_bitop3_b32 v4, s35, 56, v163 bitop3:0xc8
	global_load_lds_dwordx4 v[2:3], off
	v_lshlrev_b32_e32 v138, 2, v4
	v_lshl_add_u64 v[6:7], s[16:17], 0, v[138:139]
	s_mov_b64 s[16:17], 0x18200000
	v_lshl_add_u64 v[140:141], v[6:7], 0, s[16:17]
	s_mov_b64 s[16:17], 0x18400000
	v_lshlrev_b32_e32 v5, 10, v1
	v_lshl_add_u64 v[142:143], v[6:7], 0, s[16:17]
	v_and_b32_e32 v5, 0xe0000, v5
	v_lshlrev_b32_e32 v6, 13, v161
	v_lshlrev_b32_e32 v2, 6, v158
	s_movk_i32 s36, 0x3c0
	v_lshlrev_b32_e32 v3, 2, v158
	v_or3_b32 v5, v159, v5, v6
	v_and_or_b32 v2, v2, s36, v164
	v_and_b32_e32 v3, 32, v3
	s_cmpk_lt_u32 s12, 0x100
	v_add_u32_e32 v144, v5, v160
	v_lshlrev_b32_e32 v5, 6, v162
	v_bitop3_b32 v3, v2, s13, v3 bitop3:0xde
	v_lshl_or_b32 v164, s3, 12, v165
	s_waitcnt vmcnt(6)
	s_cselect_b64 s[12:13], -1, 0
	s_lshl_b32 s3, s34, 6
	v_and_b32_e32 v5, 0x1e0000, v5
	v_or_b32_e32 v2, s35, v163
	s_and_b32 s3, s3, 0x80
	v_or3_b32 v5, v159, v5, v6
	s_add_i32 s73, 0, 0x10000
	s_add_i32 s74, 0, 0x14000
	v_or_b32_e32 v163, 16, v158
	v_or_b32_e32 v165, 32, v158
	v_or_b32_e32 v166, 48, v158
	v_mov_b32_e32 v145, v139
	v_add_u32_e32 v146, v5, v160
	v_mov_b32_e32 v147, v139
	s_movk_i32 s72, 0xa1
	v_add_u32_e32 v159, s73, v164
	v_add_u32_e32 v160, s74, v164
	v_add_u32_e32 v161, 0, v3
	s_lshl_b32 s75, s3, 1
	v_lshlrev_b32_e32 v138, 1, v2
	v_lshlrev_b32_e32 v148, 1, v4
	s_movk_i32 s76, 0xfcf
	s_movk_i32 s77, 0xfef
	v_mov_b64_e32 v[150:151], 0x4ff
	v_mov_b32_e32 v162, 0xfdf
	v_mov_b32_e32 v167, 0xfff
	s_barrier
	s_branch .LBB0_213

; #define PG8_STAGE(bufoff, gbase, voff) do { _Pragma("unroll") for (int _i = 0; _i < 2; ++_i) \
;         __builtin_amdgcn_global_load_lds((const unsigned*)((const char*)(gbase) + (voff)[_i]), (PG8_LAS unsigned*)(lds + (bufoff) + ldsw + _i * 8192), 16, 0, 0); } while (0)
; #define PG8_LDA(dst, b, h) do { _Pragma("unroll") for (int m = 0; m < 4; ++m) _Pragma("unroll") for (int k = 0; k < 2; ++k) dst[m][k] = *(const PG8_LAS bf16x8*)(lds + PG8_SA(b, h) + aoff + m * 2048 + k * 1024); } while (0)
; #define PG8_LDB(dst, b, h) do { _Pragma("unroll") for (int n = 0; n < 2; ++n) _Pragma("unroll") for (int k = 0; k < 2; ++k) dst[n][k] = *(const PG8_LAS bf16x8*)(lds + PG8_SB(b, h) + boff + n * 2048 + k * 1024); } while (0)
; #define PG8_MMA(ai, bj, At, Bt) do { __builtin_amdgcn_s_setprio(1); _Pragma("unroll") for (int m = 0; m < 4; ++m) _Pragma("unroll") for (int n = 0; n < 2; ++n) _Pragma("unroll") for (int k = 0; k < 2; ++k) \
;         acc[ai][bj][m][n] = __builtin_amdgcn_mfma_f32_16x16x32_bf16(Bt[n][k], At[m][k], acc[ai][bj][m][n], 0, 0, 0); __builtin_amdgcn_s_setprio(0); } while (0)
; #define PG8_WAIT_V(n) asm volatile("s_waitcnt vmcnt(" #n ")" ::: "memory")
; #define PG8_WAIT_L(n) asm volatile("s_waitcnt lgkmcnt(" #n ")" ::: "memory")
; #define PG8_BAR __builtin_amdgcn_s_barrier()
; #define PG8_SCHED __builtin_amdgcn_sched_barrier(0)
; template <class Epi, class Sched, bool ALIGN_EPI = false, bool SP2 = false>
; __device__ __forceinline__ void gemm_phase(PG8_LAS unsigned char* lds, const Gemm g, const Sched& S, const Epi& E) {
;     ...
;             PG8_LDB(B0, 0, 0); PG8_LDB(B1, 0, 1); PG8_SCHED; PG8_LDA(At, 0, 0); PG8_STAGE(PG8_SA(1, 1), a1 + hstep, voffA);
;             PG8_WAIT_V(8); PG8_WAIT_L(0); PG8_BAR; PG8_MMA(0, 0, At, B0); PG8_MMA(0, 1, At, B1); PG8_BAR; PG8_SCHED;
;             PG8_LDA(At, 0, 1); PG8_STAGE(PG8_SB(0, 0), b2, voffB); PG8_STAGE(PG8_SB(0, 1), b2 + hstep, voffB); PG8_STAGE(PG8_SA(0, 0), a2, voffA);
.LBB0_217:
	ds_read_b128 v[152:155], v159
	ds_read_b128 v[168:171], v159 offset:1024
	ds_read_b128 v[172:175], v159 offset:2048
	ds_read_b128 v[176:179], v159 offset:3072
	ds_read_b128 v[180:183], v160
	ds_read_b128 v[184:187], v160 offset:1024
	ds_read_b128 v[188:191], v160 offset:2048
	ds_read_b128 v[192:195], v160 offset:3072
	s_add_u32 s46, s44, 0xfff00080
	s_addc_u32 s47, s45, -1
	s_cmp_eq_u32 s80, 60
	s_cselect_b32 s49, s3, s47
	s_cselect_b32 s48, s35, s46
	s_cselect_b32 s47, s17, s79
	s_cselect_b32 s46, s43, s78
	v_lshl_add_u64 v[156:157], v[232:233], 0, s[10:11]
	s_mov_b32 m0, s70
	s_nop 0
	global_load_lds_dwordx4 v[156:157], off
	v_lshl_add_u64 v[156:157], v[234:235], 0, s[10:11]
	s_mov_b32 m0, s71
	s_nop 0
	global_load_lds_dwordx4 v[156:157], off
	v_lshl_add_u64 v[156:157], s[44:45], 0, v[144:145]
	s_add_i32 m0, s56, 0xc000
	ds_read_b128 v[198:201], v161
	ds_read_b128 v[202:205], v161 offset:1024
	ds_read_b128 v[206:209], v161 offset:2048
	ds_read_b128 v[210:213], v161 offset:3072
	ds_read_b128 v[214:217], v161 offset:4096
	ds_read_b128 v[218:221], v161 offset:5120
	ds_read_b128 v[222:225], v161 offset:6144
	ds_read_b128 v[226:229], v161 offset:7168
	global_load_lds_dwordx4 v[156:157], off
	v_lshl_add_u64 v[156:157], s[44:45], 0, v[146:147]
	s_add_i32 m0, s56, 0xe000
	s_nop 0
	global_load_lds_dwordx4 v[156:157], off
	s_waitcnt vmcnt(8)
	s_waitcnt lgkmcnt(0)
	s_barrier
	s_setprio 1
	s_waitcnt lgkmcnt(0)
	v_mfma_f32_16x16x32_bf16 v[126:129], v[152:155], v[198:201], v[126:129]
	v_mfma_f32_16x16x32_bf16 v[122:125], v[172:175], v[198:201], v[122:125]
	v_mfma_f32_16x16x32_bf16 v[110:113], v[152:155], v[206:209], v[110:113]
	v_mfma_f32_16x16x32_bf16 v[106:109], v[172:175], v[206:209], v[106:109]
	v_mfma_f32_16x16x32_bf16 v[94:97], v[152:155], v[214:217], v[94:97]
	v_mfma_f32_16x16x32_bf16 v[90:93], v[172:175], v[214:217], v[90:93]
	v_mfma_f32_16x16x32_bf16 v[78:81], v[152:155], v[222:225], v[78:81]
	v_mfma_f32_16x16x32_bf16 v[74:77], v[172:175], v[222:225], v[74:77]
	v_mfma_f32_16x16x32_bf16 v[126:129], v[168:171], v[202:205], v[126:129]
	v_mfma_f32_16x16x32_bf16 v[122:125], v[176:179], v[202:205], v[122:125]
	v_mfma_f32_16x16x32_bf16 v[110:113], v[168:171], v[210:213], v[110:113]
	v_mfma_f32_16x16x32_bf16 v[106:109], v[176:179], v[210:213], v[106:109]
	v_mfma_f32_16x16x32_bf16 v[94:97], v[168:171], v[218:221], v[94:97]
	v_mfma_f32_16x16x32_bf16 v[90:93], v[176:179], v[218:221], v[90:93]
	v_mfma_f32_16x16x32_bf16 v[78:81], v[168:171], v[226:229], v[78:81]
	v_mfma_f32_16x16x32_bf16 v[74:77], v[176:179], v[226:229], v[74:77]
	s_setprio 0
	s_setprio 1
	v_mfma_f32_16x16x32_bf16 v[118:121], v[180:183], v[198:201], v[118:121]
	v_mfma_f32_16x16x32_bf16 v[114:117], v[188:191], v[198:201], v[114:117]
	v_mfma_f32_16x16x32_bf16 v[102:105], v[180:183], v[206:209], v[102:105]
	v_mfma_f32_16x16x32_bf16 v[98:101], v[188:191], v[206:209], v[98:101]
	v_mfma_f32_16x16x32_bf16 v[86:89], v[180:183], v[214:217], v[86:89]
	v_mfma_f32_16x16x32_bf16 v[82:85], v[188:191], v[214:217], v[82:85]
	v_mfma_f32_16x16x32_bf16 v[70:73], v[180:183], v[222:225], v[70:73]
	v_mfma_f32_16x16x32_bf16 v[66:69], v[188:191], v[222:225], v[66:69]
	v_mfma_f32_16x16x32_bf16 v[118:121], v[184:187], v[202:205], v[118:121]
	v_mfma_f32_16x16x32_bf16 v[114:117], v[192:195], v[202:205], v[114:117]
	v_mfma_f32_16x16x32_bf16 v[102:105], v[184:187], v[210:213], v[102:105]
	v_mfma_f32_16x16x32_bf16 v[98:101], v[192:195], v[210:213], v[98:101]
	v_mfma_f32_16x16x32_bf16 v[86:89], v[184:187], v[218:221], v[86:89]
	v_mfma_f32_16x16x32_bf16 v[82:85], v[192:195], v[218:221], v[82:85]
	v_mfma_f32_16x16x32_bf16 v[70:73], v[184:187], v[226:229], v[70:73]
	v_mfma_f32_16x16x32_bf16 v[66:69], v[192:195], v[226:229], v[66:69]
	s_setprio 0
	s_barrier
	s_add_i32 s81, s73, s55
	v_lshl_add_u64 v[156:157], s[46:47], 0, v[132:133]
	s_mov_b32 m0, s81
	ds_read_b128 v[198:201], v161 offset:16384
	ds_read_b128 v[202:205], v161 offset:17408
	ds_read_b128 v[206:209], v161 offset:18432
	ds_read_b128 v[210:213], v161 offset:19456
	ds_read_b128 v[214:217], v161 offset:20480
	ds_read_b128 v[218:221], v161 offset:21504
	ds_read_b128 v[222:225], v161 offset:22528
	ds_read_b128 v[226:229], v161 offset:23552
	global_load_lds_dwordx4 v[156:157], off
	s_add_i32 m0, s81, 0x2000
	s_add_u32 s82, s46, 0x100000
	v_lshl_add_u64 v[230:231], s[46:47], 0, v[136:137]
	s_addc_u32 s83, s47, 0
	s_add_i32 s81, s74, s55
	global_load_lds_dwordx4 v[230:231], off
	v_lshl_add_u64 v[232:233], s[82:83], 0, v[132:133]
	s_mov_b32 m0, s81
	v_lshl_add_u64 v[234:235], s[48:49], 0, v[134:135]
	global_load_lds_dwordx4 v[232:233], off
	v_lshl_add_u64 v[232:233], s[82:83], 0, v[136:137]
	s_add_i32 m0, s81, 0x2000
	s_nop 0
	global_load_lds_dwordx4 v[232:233], off
	v_lshl_add_u64 v[232:233], s[48:49], 0, v[130:131]
	s_waitcnt vmcnt(6)
	s_waitcnt lgkmcnt(0)
	s_barrier
; #define PG8_STAGE(bufoff, gbase, voff) do { _Pragma("unroll") for (int _i = 0; _i < 2; ++_i) \
;         __builtin_amdgcn_global_load_lds((const unsigned*)((const char*)(gbase) + (voff)[_i]), (PG8_LAS unsigned*)(lds + (bufoff) + ldsw + _i * 8192), 16, 0, 0); } while (0)
; #define PG8_LDA(dst, b, h) do { _Pragma("unroll") for (int m = 0; m < 4; ++m) _Pragma("unroll") for (int k = 0; k < 2; ++k) dst[m][k] = *(const PG8_LAS bf16x8*)(lds + PG8_SA(b, h) + aoff + m * 2048 + k * 1024); } while (0)
; #define PG8_LDB(dst, b, h) do { _Pragma("unroll") for (int n = 0; n < 2; ++n) _Pragma("unroll") for (int k = 0; k < 2; ++k) dst[n][k] = *(const PG8_LAS bf16x8*)(lds + PG8_SB(b, h) + boff + n * 2048 + k * 1024); } while (0)
; #define PG8_MMA(ai, bj, At, Bt) do { __builtin_amdgcn_s_setprio(1); _Pragma("unroll") for (int m = 0; m < 4; ++m) _Pragma("unroll") for (int n = 0; n < 2; ++n) _Pragma("unroll") for (int k = 0; k < 2; ++k) \
;         acc[ai][bj][m][n] = __builtin_amdgcn_mfma_f32_16x16x32_bf16(Bt[n][k], At[m][k], acc[ai][bj][m][n], 0, 0, 0); __builtin_amdgcn_s_setprio(0); } while (0)
; #define PG8_WAIT_V(n) asm volatile("s_waitcnt vmcnt(" #n ")" ::: "memory")
; #define PG8_WAIT_L(n) asm volatile("s_waitcnt lgkmcnt(" #n ")" ::: "memory")
; #define PG8_BAR __builtin_amdgcn_s_barrier()
; #define PG8_SCHED __builtin_amdgcn_sched_barrier(0)
; template <class Epi, class Sched, bool ALIGN_EPI = false, bool SP2 = false>
; __device__ __forceinline__ void gemm_phase(PG8_LAS unsigned char* lds, const Gemm g, const Sched& S, const Epi& E) {
;     ...
;             PG8_LDA(At, 0, 1); PG8_STAGE(PG8_SB(0, 0), b2, voffB); PG8_STAGE(PG8_SB(0, 1), b2 + hstep, voffB); PG8_STAGE(PG8_SA(0, 0), a2, voffA);
;             PG8_WAIT_V(8); PG8_WAIT_L(0); PG8_BAR; PG8_MMA(1, 0, At, B0); PG8_MMA(1, 1, At, B1); PG8_BAR; PG8_SCHED;
;             PG8_LDB(B0, 1, 0); PG8_LDB(B1, 1, 1); PG8_SCHED; PG8_LDA(At, 1, 0); PG8_STAGE(PG8_SA(0, 1), a2 + hstep, voffA);
	s_setprio 1
	s_waitcnt lgkmcnt(0)
	v_mfma_f32_16x16x32_bf16 v[62:65], v[152:155], v[198:201], v[62:65]
	v_mfma_f32_16x16x32_bf16 v[58:61], v[172:175], v[198:201], v[58:61]
	v_mfma_f32_16x16x32_bf16 v[46:49], v[152:155], v[206:209], v[46:49]
	v_mfma_f32_16x16x32_bf16 v[42:45], v[172:175], v[206:209], v[42:45]
	v_mfma_f32_16x16x32_bf16 v[30:33], v[152:155], v[214:217], v[30:33]
	v_mfma_f32_16x16x32_bf16 v[26:29], v[172:175], v[214:217], v[26:29]
	v_mfma_f32_16x16x32_bf16 v[14:17], v[152:155], v[222:225], v[14:17]
	v_mfma_f32_16x16x32_bf16 v[10:13], v[172:175], v[222:225], v[10:13]
	v_mfma_f32_16x16x32_bf16 v[62:65], v[168:171], v[202:205], v[62:65]
	v_mfma_f32_16x16x32_bf16 v[58:61], v[176:179], v[202:205], v[58:61]
	v_mfma_f32_16x16x32_bf16 v[46:49], v[168:171], v[210:213], v[46:49]
	v_mfma_f32_16x16x32_bf16 v[42:45], v[176:179], v[210:213], v[42:45]
	v_mfma_f32_16x16x32_bf16 v[30:33], v[168:171], v[218:221], v[30:33]
	v_mfma_f32_16x16x32_bf16 v[26:29], v[176:179], v[218:221], v[26:29]
	v_mfma_f32_16x16x32_bf16 v[14:17], v[168:171], v[226:229], v[14:17]
	v_mfma_f32_16x16x32_bf16 v[10:13], v[176:179], v[226:229], v[10:13]
	s_setprio 0
	s_setprio 1
	v_mfma_f32_16x16x32_bf16 v[54:57], v[180:183], v[198:201], v[54:57]
	v_mfma_f32_16x16x32_bf16 v[50:53], v[188:191], v[198:201], v[50:53]
	v_mfma_f32_16x16x32_bf16 v[38:41], v[180:183], v[206:209], v[38:41]
	v_mfma_f32_16x16x32_bf16 v[34:37], v[188:191], v[206:209], v[34:37]
	v_mfma_f32_16x16x32_bf16 v[22:25], v[180:183], v[214:217], v[22:25]
	v_mfma_f32_16x16x32_bf16 v[18:21], v[188:191], v[214:217], v[18:21]
	v_mfma_f32_16x16x32_bf16 v[6:9], v[180:183], v[222:225], v[6:9]
	v_mfma_f32_16x16x32_bf16 v[2:5], v[188:191], v[222:225], v[2:5]
	v_mfma_f32_16x16x32_bf16 v[54:57], v[184:187], v[202:205], v[54:57]
	v_mfma_f32_16x16x32_bf16 v[50:53], v[192:195], v[202:205], v[50:53]
	v_mfma_f32_16x16x32_bf16 v[38:41], v[184:187], v[210:213], v[38:41]
	v_mfma_f32_16x16x32_bf16 v[34:37], v[192:195], v[210:213], v[34:37]
	v_mfma_f32_16x16x32_bf16 v[22:25], v[184:187], v[218:221], v[22:25]
	v_mfma_f32_16x16x32_bf16 v[18:21], v[192:195], v[218:221], v[18:21]
	v_mfma_f32_16x16x32_bf16 v[6:9], v[184:187], v[226:229], v[6:9]
	v_mfma_f32_16x16x32_bf16 v[2:5], v[192:195], v[226:229], v[2:5]
	s_setprio 0
	s_barrier
	s_add_i32 s81, 0, 0x18000
	v_add_u32_e32 v149, s81, v164
	s_add_i32 s82, 0, 0x1c000
	ds_read_b128 v[152:155], v149
	ds_read_b128 v[168:171], v149 offset:1024
	ds_read_b128 v[172:175], v149 offset:2048
	ds_read_b128 v[176:179], v149 offset:3072
	v_add_u32_e32 v149, s82, v164
	ds_read_b128 v[180:183], v149
	ds_read_b128 v[184:187], v149 offset:1024
	ds_read_b128 v[188:191], v149 offset:2048
	ds_read_b128 v[192:195], v149 offset:3072
	s_add_u32 s48, s48, 0x100000
	s_addc_u32 s49, s49, 0
	s_mov_b32 m0, s56
	s_nop 0
	global_load_lds_dwordx4 v[232:233], off
	s_mov_b32 m0, s57
	s_nop 0
	global_load_lds_dwordx4 v[234:235], off
	s_mov_b32 m0, s58
	v_lshl_add_u64 v[236:237], s[48:49], 0, v[130:131]
	ds_read_b128 v[198:201], v161 offset:32768
	ds_read_b128 v[202:205], v161 offset:33792
	ds_read_b128 v[206:209], v161 offset:34816
	ds_read_b128 v[210:213], v161 offset:35840
	ds_read_b128 v[214:217], v161 offset:36864
	ds_read_b128 v[218:221], v161 offset:37888
	ds_read_b128 v[222:225], v161 offset:38912
	ds_read_b128 v[226:229], v161 offset:39936
	global_load_lds_dwordx4 v[236:237], off
	v_lshl_add_u64 v[236:237], s[48:49], 0, v[134:135]
	s_mov_b32 m0, s59
	s_nop 0
	global_load_lds_dwordx4 v[236:237], off
	s_waitcnt vmcnt(8)
	s_waitcnt lgkmcnt(0)
	s_barrier
; #define PG8_STAGE(bufoff, gbase, voff) do { _Pragma("unroll") for (int _i = 0; _i < 2; ++_i) \
;         __builtin_amdgcn_global_load_lds((const unsigned*)((const char*)(gbase) + (voff)[_i]), (PG8_LAS unsigned*)(lds + (bufoff) + ldsw + _i * 8192), 16, 0, 0); } while (0)
; #define PG8_LDA(dst, b, h) do { _Pragma("unroll") for (int m = 0; m < 4; ++m) _Pragma("unroll") for (int k = 0; k < 2; ++k) dst[m][k] = *(const PG8_LAS bf16x8*)(lds + PG8_SA(b, h) + aoff + m * 2048 + k * 1024); } while (0)
; #define PG8_LDB(dst, b, h) do { _Pragma("unroll") for (int n = 0; n < 2; ++n) _Pragma("unroll") for (int k = 0; k < 2; ++k) dst[n][k] = *(const PG8_LAS bf16x8*)(lds + PG8_SB(b, h) + boff + n * 2048 + k * 1024); } while (0)
; #define PG8_MMA(ai, bj, At, Bt) do { __builtin_amdgcn_s_setprio(1); _Pragma("unroll") for (int m = 0; m < 4; ++m) _Pragma("unroll") for (int n = 0; n < 2; ++n) _Pragma("unroll") for (int k = 0; k < 2; ++k) \
;         acc[ai][bj][m][n] = __builtin_amdgcn_mfma_f32_16x16x32_bf16(Bt[n][k], At[m][k], acc[ai][bj][m][n], 0, 0, 0); __builtin_amdgcn_s_setprio(0); } while (0)
; #define PG8_WAIT_V(n) asm volatile("s_waitcnt vmcnt(" #n ")" ::: "memory")
; #define PG8_WAIT_L(n) asm volatile("s_waitcnt lgkmcnt(" #n ")" ::: "memory")
; #define PG8_BAR __builtin_amdgcn_s_barrier()
; #define PG8_SCHED __builtin_amdgcn_sched_barrier(0)
; template <class Epi, class Sched, bool ALIGN_EPI = false, bool SP2 = false>
; __device__ __forceinline__ void gemm_phase(PG8_LAS unsigned char* lds, const Gemm g, const Sched& S, const Epi& E) {
;     ...
;             PG8_LDB(B0, 1, 0); PG8_LDB(B1, 1, 1); PG8_SCHED; PG8_LDA(At, 1, 0); PG8_STAGE(PG8_SA(0, 1), a2 + hstep, voffA);
;             PG8_WAIT_V(8); PG8_WAIT_L(0); PG8_BAR; PG8_MMA(0, 0, At, B0); PG8_MMA(0, 1, At, B1); PG8_BAR; PG8_SCHED;
;             PG8_LDA(At, 1, 1); PG8_STAGE(PG8_SB(1, 0), b3, voffB); PG8_STAGE(PG8_SB(1, 1), b3 + hstep, voffB); PG8_STAGE(PG8_SA(1, 0), a3, voffA);
;             PG8_WAIT_V(8); PG8_WAIT_L(0); PG8_BAR; PG8_MMA(1, 0, At, B0); PG8_MMA(1, 1, At, B1); PG8_BAR; PG8_SCHED;
	s_setprio 1
	s_waitcnt lgkmcnt(0)
	v_mfma_f32_16x16x32_bf16 v[126:129], v[152:155], v[198:201], v[126:129]
	v_mfma_f32_16x16x32_bf16 v[122:125], v[172:175], v[198:201], v[122:125]
	v_mfma_f32_16x16x32_bf16 v[110:113], v[152:155], v[206:209], v[110:113]
	v_mfma_f32_16x16x32_bf16 v[106:109], v[172:175], v[206:209], v[106:109]
	v_mfma_f32_16x16x32_bf16 v[94:97], v[152:155], v[214:217], v[94:97]
	v_mfma_f32_16x16x32_bf16 v[90:93], v[172:175], v[214:217], v[90:93]
	v_mfma_f32_16x16x32_bf16 v[78:81], v[152:155], v[222:225], v[78:81]
	v_mfma_f32_16x16x32_bf16 v[74:77], v[172:175], v[222:225], v[74:77]
	v_mfma_f32_16x16x32_bf16 v[126:129], v[168:171], v[202:205], v[126:129]
	v_mfma_f32_16x16x32_bf16 v[122:125], v[176:179], v[202:205], v[122:125]
	v_mfma_f32_16x16x32_bf16 v[110:113], v[168:171], v[210:213], v[110:113]
	v_mfma_f32_16x16x32_bf16 v[106:109], v[176:179], v[210:213], v[106:109]
	v_mfma_f32_16x16x32_bf16 v[94:97], v[168:171], v[218:221], v[94:97]
	v_mfma_f32_16x16x32_bf16 v[90:93], v[176:179], v[218:221], v[90:93]
	v_mfma_f32_16x16x32_bf16 v[78:81], v[168:171], v[226:229], v[78:81]
	v_mfma_f32_16x16x32_bf16 v[74:77], v[176:179], v[226:229], v[74:77]
	s_setprio 0
	s_setprio 1
	v_mfma_f32_16x16x32_bf16 v[118:121], v[180:183], v[198:201], v[118:121]
	v_mfma_f32_16x16x32_bf16 v[114:117], v[188:191], v[198:201], v[114:117]
	v_mfma_f32_16x16x32_bf16 v[102:105], v[180:183], v[206:209], v[102:105]
	v_mfma_f32_16x16x32_bf16 v[98:101], v[188:191], v[206:209], v[98:101]
	v_mfma_f32_16x16x32_bf16 v[86:89], v[180:183], v[214:217], v[86:89]
	v_mfma_f32_16x16x32_bf16 v[82:85], v[188:191], v[214:217], v[82:85]
	v_mfma_f32_16x16x32_bf16 v[70:73], v[180:183], v[222:225], v[70:73]
	v_mfma_f32_16x16x32_bf16 v[66:69], v[188:191], v[222:225], v[66:69]
	v_mfma_f32_16x16x32_bf16 v[118:121], v[184:187], v[202:205], v[118:121]
	v_mfma_f32_16x16x32_bf16 v[114:117], v[192:195], v[202:205], v[114:117]
	v_mfma_f32_16x16x32_bf16 v[102:105], v[184:187], v[210:213], v[102:105]
	v_mfma_f32_16x16x32_bf16 v[98:101], v[192:195], v[210:213], v[98:101]
	v_mfma_f32_16x16x32_bf16 v[86:89], v[184:187], v[218:221], v[86:89]
	v_mfma_f32_16x16x32_bf16 v[82:85], v[192:195], v[218:221], v[82:85]
	v_mfma_f32_16x16x32_bf16 v[70:73], v[184:187], v[226:229], v[70:73]
	v_mfma_f32_16x16x32_bf16 v[66:69], v[192:195], v[226:229], v[66:69]
	s_setprio 0
	s_barrier
	s_add_i32 s48, s81, s55
	v_lshl_add_u64 v[156:157], v[156:157], 0, s[10:11]
	s_mov_b32 m0, s48
	ds_read_b128 v[198:201], v161 offset:49152
	ds_read_b128 v[202:205], v161 offset:50176
	ds_read_b128 v[206:209], v161 offset:51200
	ds_read_b128 v[210:213], v161 offset:52224
	ds_read_b128 v[214:217], v161 offset:53248
	ds_read_b128 v[218:221], v161 offset:54272
	ds_read_b128 v[222:225], v161 offset:55296
	ds_read_b128 v[226:229], v161 offset:56320
	global_load_lds_dwordx4 v[156:157], off
	s_add_i32 m0, s48, 0x2000
	s_add_u32 s46, s46, 0x100080
	v_lshl_add_u64 v[156:157], v[230:231], 0, s[10:11]
	s_addc_u32 s47, s47, 0
	s_add_i32 s48, s82, s55
	global_load_lds_dwordx4 v[156:157], off
	v_lshl_add_u64 v[156:157], s[46:47], 0, v[132:133]
	s_mov_b32 m0, s48
	s_nop 0
	global_load_lds_dwordx4 v[156:157], off
	v_lshl_add_u64 v[156:157], s[46:47], 0, v[136:137]
	s_add_i32 m0, s48, 0x2000
	s_nop 0
	global_load_lds_dwordx4 v[156:157], off
	s_waitcnt vmcnt(6)
	s_waitcnt lgkmcnt(0)
	s_barrier
	s_setprio 1
	s_waitcnt lgkmcnt(0)
	v_mfma_f32_16x16x32_bf16 v[62:65], v[152:155], v[198:201], v[62:65]
	v_mfma_f32_16x16x32_bf16 v[58:61], v[172:175], v[198:201], v[58:61]
	v_mfma_f32_16x16x32_bf16 v[46:49], v[152:155], v[206:209], v[46:49]
	v_mfma_f32_16x16x32_bf16 v[42:45], v[172:175], v[206:209], v[42:45]
	v_mfma_f32_16x16x32_bf16 v[30:33], v[152:155], v[214:217], v[30:33]
	v_mfma_f32_16x16x32_bf16 v[26:29], v[172:175], v[214:217], v[26:29]
	v_mfma_f32_16x16x32_bf16 v[14:17], v[152:155], v[222:225], v[14:17]
	v_mfma_f32_16x16x32_bf16 v[10:13], v[172:175], v[222:225], v[10:13]
	v_mfma_f32_16x16x32_bf16 v[62:65], v[168:171], v[202:205], v[62:65]
	v_mfma_f32_16x16x32_bf16 v[58:61], v[176:179], v[202:205], v[58:61]
	v_mfma_f32_16x16x32_bf16 v[46:49], v[168:171], v[210:213], v[46:49]
	v_mfma_f32_16x16x32_bf16 v[42:45], v[176:179], v[210:213], v[42:45]
	v_mfma_f32_16x16x32_bf16 v[30:33], v[168:171], v[218:221], v[30:33]
	v_mfma_f32_16x16x32_bf16 v[26:29], v[176:179], v[218:221], v[26:29]
	v_mfma_f32_16x16x32_bf16 v[14:17], v[168:171], v[226:229], v[14:17]
	v_mfma_f32_16x16x32_bf16 v[10:13], v[176:179], v[226:229], v[10:13]
	s_setprio 0
	s_setprio 1
	v_mfma_f32_16x16x32_bf16 v[54:57], v[180:183], v[198:201], v[54:57]
	v_mfma_f32_16x16x32_bf16 v[50:53], v[188:191], v[198:201], v[50:53]
	v_mfma_f32_16x16x32_bf16 v[38:41], v[180:183], v[206:209], v[38:41]
	v_mfma_f32_16x16x32_bf16 v[34:37], v[188:191], v[206:209], v[34:37]
	v_mfma_f32_16x16x32_bf16 v[22:25], v[180:183], v[214:217], v[22:25]
	v_mfma_f32_16x16x32_bf16 v[18:21], v[188:191], v[214:217], v[18:21]
	v_mfma_f32_16x16x32_bf16 v[6:9], v[180:183], v[222:225], v[6:9]
	v_mfma_f32_16x16x32_bf16 v[2:5], v[188:191], v[222:225], v[2:5]
	v_mfma_f32_16x16x32_bf16 v[54:57], v[184:187], v[202:205], v[54:57]
	v_mfma_f32_16x16x32_bf16 v[50:53], v[192:195], v[202:205], v[50:53]
	v_mfma_f32_16x16x32_bf16 v[38:41], v[184:187], v[210:213], v[38:41]
	v_mfma_f32_16x16x32_bf16 v[34:37], v[192:195], v[210:213], v[34:37]
	v_mfma_f32_16x16x32_bf16 v[22:25], v[184:187], v[218:221], v[22:25]
	v_mfma_f32_16x16x32_bf16 v[18:21], v[192:195], v[218:221], v[18:21]
	v_mfma_f32_16x16x32_bf16 v[6:9], v[184:187], v[226:229], v[6:9]
	v_mfma_f32_16x16x32_bf16 v[2:5], v[192:195], v[226:229], v[2:5]
	s_setprio 0
	s_barrier
	s_add_i32 s80, s80, 2
	s_add_u32 s44, s44, 0x100
	s_addc_u32 s45, s45, 0
	s_add_u32 s78, s78, 0x100
	s_addc_u32 s79, s79, 0
	s_cmp_gt_u32 s80, 61
	s_cbranch_scc0 .LBB0_217
	s_and_b64 vcc, exec, s[12:13]
	s_cbranch_vccz .LBB0_220
	s_barrier

; #define PG8_STAGE(bufoff, gbase, voff) do { _Pragma("unroll") for (int _i = 0; _i < 2; ++_i) \
;         __builtin_amdgcn_global_load_lds((const unsigned*)((const char*)(gbase) + (voff)[_i]), (PG8_LAS unsigned*)(lds + (bufoff) + ldsw + _i * 8192), 16, 0, 0); } while (0)
; #define PG8_WAIT_V(n) asm volatile("s_waitcnt vmcnt(" #n ")" ::: "memory")
; #define PG8_BAR __builtin_amdgcn_s_barrier()
; template <class Epi, class Sched, bool ALIGN_EPI = false, bool SP2 = false>
; __device__ __forceinline__ void gemm_phase(PG8_LAS unsigned char* lds, const Gemm g, const Sched& S, const Epi& E) {
;     ...
;     const unsigned ldsw = (unsigned)wid * 1024u;
;     const int aoff = lds_byte(wr * 64 + fr, fq * 8), boff = lds_byte(wc * 32 + fr, fq * 8);
;     ...
;         PG8_STAGE(PG8_SB(1, 0), cB + kstep, voffB); PG8_STAGE(PG8_SA(1, 0), cA + kstep, voffA); PG8_STAGE(PG8_SB(1, 1), cB + hstep + kstep, voffB);
;         PG8_WAIT_V(6); PG8_BAR;
.LBB0_700:
	s_add_u32 s16, s2, 0x27e00000
	s_addc_u32 s17, s3, 0
	s_add_u32 s34, s2, 0x18800000
	s_mov_b64 s[36:37], 0x80
	s_addc_u32 s35, s3, 0
	s_and_b32 s60, s5, 3
	s_add_i32 m0, s9, 0x18000
	v_lshl_add_u64 v[8:9], v[8:9], 0, s[36:37]
	s_lshl_b32 s5, s4, 13
	s_lshl_b32 s39, s60, 12
	s_waitcnt vmcnt(2)
	s_barrier
	global_load_lds_dwordx4 v[8:9], off
	v_lshl_add_u64 v[6:7], v[6:7], 0, s[36:37]
	s_add_i32 m0, s9, 0x1a000
	s_add_i32 s61, s9, 0x8000
	s_add_i32 s62, s9, 0xa000
	global_load_lds_dwordx4 v[6:7], off
	v_mov_b32_e32 v230, v2
	v_mov_b32_e32 v231, v3
	v_lshl_add_u64 v[2:3], v[2:3], 0, s[36:37]
	s_mov_b32 m0, s61
	s_add_u32 s2, s50, 0x100080
	global_load_lds_dwordx4 v[2:3], off
	v_mov_b32_e32 v232, v4
	v_mov_b32_e32 v233, v5
	v_lshl_add_u64 v[2:3], v[4:5], 0, s[36:37]
	s_mov_b32 m0, s62
	s_addc_u32 s3, s51, 0
	global_load_lds_dwordx4 v[2:3], off
	s_add_i32 m0, s9, 0x1c000
	v_lshl_add_u64 v[2:3], s[2:3], 0, v[132:133]
	global_load_lds_dwordx4 v[2:3], off
	v_lshl_add_u64 v[2:3], s[2:3], 0, v[136:137]
	s_add_i32 m0, s9, 0x1e000
	v_lshlrev_b32_e32 v7, 6, v1
	global_load_lds_dwordx4 v[2:3], off
	v_bfe_u32 v2, v1, 4, 2
	v_and_b32_e32 v3, 15, v1
	v_lshlrev_b32_e32 v5, 4, v2
	s_movk_i32 s2, 0x3c0
	v_lshl_or_b32 v150, s4, 6, v3
	v_lshlrev_b32_e32 v4, 3, v2
	v_lshl_or_b32 v3, v3, 6, v5
	v_and_or_b32 v5, v7, s2, v5
	v_cmp_eq_u32_e64 s[2:3], 0, v2
	v_lshlrev_b32_e32 v2, 10, v1
	v_lshl_or_b32 v152, s60, 5, v4
	v_and_b32_e32 v2, 0xe0000, v2
	v_lshlrev_b32_e32 v4, 13, v12
	v_or3_b32 v2, v10, v2, v4
	v_add_u32_e32 v138, v2, v11
	v_lshlrev_b32_e32 v2, 6, v13
	v_lshlrev_b32_e32 v6, 2, v1
	v_and_b32_e32 v2, 0x1e0000, v2
	v_and_b32_e32 v6, 32, v6
	s_waitcnt vmcnt(6)
	s_cmpk_lt_u32 s38, 0x100
	v_or3_b32 v2, v10, v2, v4
	v_bitop3_b32 v3, v3, s5, v6 bitop3:0xde
	v_bitop3_b32 v151, s39, v5, v6 bitop3:0xf6
	s_cselect_b64 s[38:39], -1, 0
	v_add_u32_e32 v140, v2, v11
	s_add_i32 s69, 0, 0x10000
	s_add_i32 s70, 0, 0x14000
	v_mbcnt_lo_u32_b32 v2, -1, 0
	v_or_b32_e32 v153, 16, v150
	v_or_b32_e32 v154, 32, v150
	v_or_b32_e32 v155, 48, v150
	v_add_u32_e32 v156, 0x80, v150
	v_add_u32_e32 v157, 0x90, v150
	v_add_u32_e32 v158, 0xa0, v150
	v_add_u32_e32 v159, 0xb0, v150
	s_ashr_i32 s63, s22, 31
	s_mov_b32 s67, s22
	s_ashr_i32 s68, s14, 31
	v_mov_b32_e32 v139, v133
	v_mov_b32_e32 v141, v133
	v_mov_b64_e32 v[142:143], 0x200
	v_mov_b64_e32 v[144:145], 0x1ff
	v_add_u32_e32 v160, s69, v151
	v_add_u32_e32 v161, s70, v151
	v_add_u32_e32 v162, 0, v3
	v_mbcnt_hi_u32_b32 v163, -1, v2
	s_mov_b32 s71, 0
	s_barrier
	s_branch .LBB0_703

; #define PG8_STAGE(bufoff, gbase, voff) do { _Pragma("unroll") for (int _i = 0; _i < 2; ++_i) \
;         __builtin_amdgcn_global_load_lds((const unsigned*)((const char*)(gbase) + (voff)[_i]), (PG8_LAS unsigned*)(lds + (bufoff) + ldsw + _i * 8192), 16, 0, 0); } while (0)
; #define PG8_LDA(dst, b, h) do { _Pragma("unroll") for (int m = 0; m < 4; ++m) _Pragma("unroll") for (int k = 0; k < 2; ++k) dst[m][k] = *(const PG8_LAS bf16x8*)(lds + PG8_SA(b, h) + aoff + m * 2048 + k * 1024); } while (0)
; #define PG8_LDB(dst, b, h) do { _Pragma("unroll") for (int n = 0; n < 2; ++n) _Pragma("unroll") for (int k = 0; k < 2; ++k) dst[n][k] = *(const PG8_LAS bf16x8*)(lds + PG8_SB(b, h) + boff + n * 2048 + k * 1024); } while (0)
; #define PG8_MMA(ai, bj, At, Bt) do { __builtin_amdgcn_s_setprio(1); _Pragma("unroll") for (int m = 0; m < 4; ++m) _Pragma("unroll") for (int n = 0; n < 2; ++n) _Pragma("unroll") for (int k = 0; k < 2; ++k) \
;         acc[ai][bj][m][n] = __builtin_amdgcn_mfma_f32_16x16x32_bf16(Bt[n][k], At[m][k], acc[ai][bj][m][n], 0, 0, 0); __builtin_amdgcn_s_setprio(0); } while (0)
; #define PG8_WAIT_V(n) asm volatile("s_waitcnt vmcnt(" #n ")" ::: "memory")
; #define PG8_WAIT_L(n) asm volatile("s_waitcnt lgkmcnt(" #n ")" ::: "memory")
; #define PG8_BAR __builtin_amdgcn_s_barrier()
; #define PG8_SCHED __builtin_amdgcn_sched_barrier(0)
; template <class Epi, class Sched, bool ALIGN_EPI = false, bool SP2 = false>
; __device__ __forceinline__ void gemm_phase(PG8_LAS unsigned char* lds, const Gemm g, const Sched& S, const Epi& E) {
;     ...
;             PG8_LDB(B0, 0, 0); PG8_LDB(B1, 0, 1); PG8_SCHED; PG8_LDA(At, 0, 0); PG8_STAGE(PG8_SA(1, 1), a1 + hstep, voffA);
;             PG8_WAIT_V(8); PG8_WAIT_L(0); PG8_BAR; PG8_MMA(0, 0, At, B0); PG8_MMA(0, 1, At, B1); PG8_BAR; PG8_SCHED;
;             PG8_LDA(At, 0, 1); PG8_STAGE(PG8_SB(0, 0), b2, voffB); PG8_STAGE(PG8_SB(0, 1), b2 + hstep, voffB); PG8_STAGE(PG8_SA(0, 0), a2, voffA);
.LBB0_710:
	ds_read_b128 v[146:149], v160
	ds_read_b128 v[164:167], v160 offset:1024
	ds_read_b128 v[168:171], v160 offset:2048
	ds_read_b128 v[172:175], v160 offset:3072
	ds_read_b128 v[176:179], v161
	ds_read_b128 v[180:183], v161 offset:1024
	ds_read_b128 v[184:187], v161 offset:2048
	ds_read_b128 v[188:191], v161 offset:3072
	s_add_u32 s50, s48, 0xfff00080
	s_addc_u32 s51, s49, -1
	s_cmp_eq_u32 s76, 60
	s_cselect_b32 s53, s43, s51
	s_cselect_b32 s52, s72, s50
	s_cselect_b32 s51, s41, s75
	s_cselect_b32 s50, s73, s74
	v_lshl_add_u64 v[226:227], v[230:231], 0, s[36:37]
	s_mov_b32 m0, s61
	s_nop 0
	global_load_lds_dwordx4 v[226:227], off
	v_lshl_add_u64 v[226:227], v[232:233], 0, s[36:37]
	s_mov_b32 m0, s62
	s_nop 0
	global_load_lds_dwordx4 v[226:227], off
	v_lshl_add_u64 v[226:227], s[48:49], 0, v[138:139]
	s_add_i32 m0, s9, 0xc000
	ds_read_b128 v[192:195], v162
	ds_read_b128 v[198:201], v162 offset:1024
	ds_read_b128 v[202:205], v162 offset:2048
	ds_read_b128 v[206:209], v162 offset:3072
	ds_read_b128 v[210:213], v162 offset:4096
	ds_read_b128 v[214:217], v162 offset:5120
	ds_read_b128 v[218:221], v162 offset:6144
	ds_read_b128 v[222:225], v162 offset:7168
	global_load_lds_dwordx4 v[226:227], off
	v_lshl_add_u64 v[226:227], s[48:49], 0, v[140:141]
	s_add_i32 m0, s9, 0xe000
	s_nop 0
	global_load_lds_dwordx4 v[226:227], off
	s_waitcnt vmcnt(8)
	s_waitcnt lgkmcnt(0)
	s_barrier
	s_setprio 1
	s_waitcnt lgkmcnt(0)
	v_mfma_f32_16x16x32_bf16 v[126:129], v[146:149], v[192:195], v[126:129]
	v_mfma_f32_16x16x32_bf16 v[122:125], v[168:171], v[192:195], v[122:125]
	v_mfma_f32_16x16x32_bf16 v[110:113], v[146:149], v[202:205], v[110:113]
	v_mfma_f32_16x16x32_bf16 v[106:109], v[168:171], v[202:205], v[106:109]
	v_mfma_f32_16x16x32_bf16 v[94:97], v[146:149], v[210:213], v[94:97]
	v_mfma_f32_16x16x32_bf16 v[90:93], v[168:171], v[210:213], v[90:93]
	v_mfma_f32_16x16x32_bf16 v[78:81], v[146:149], v[218:221], v[78:81]
	v_mfma_f32_16x16x32_bf16 v[74:77], v[168:171], v[218:221], v[74:77]
	v_mfma_f32_16x16x32_bf16 v[126:129], v[164:167], v[198:201], v[126:129]
	v_mfma_f32_16x16x32_bf16 v[122:125], v[172:175], v[198:201], v[122:125]
	v_mfma_f32_16x16x32_bf16 v[110:113], v[164:167], v[206:209], v[110:113]
	v_mfma_f32_16x16x32_bf16 v[106:109], v[172:175], v[206:209], v[106:109]
	v_mfma_f32_16x16x32_bf16 v[94:97], v[164:167], v[214:217], v[94:97]
	v_mfma_f32_16x16x32_bf16 v[90:93], v[172:175], v[214:217], v[90:93]
	v_mfma_f32_16x16x32_bf16 v[78:81], v[164:167], v[222:225], v[78:81]
	v_mfma_f32_16x16x32_bf16 v[74:77], v[172:175], v[222:225], v[74:77]
	s_setprio 0
	s_setprio 1
	v_mfma_f32_16x16x32_bf16 v[118:121], v[176:179], v[192:195], v[118:121]
	v_mfma_f32_16x16x32_bf16 v[114:117], v[184:187], v[192:195], v[114:117]
	v_mfma_f32_16x16x32_bf16 v[102:105], v[176:179], v[202:205], v[102:105]
	v_mfma_f32_16x16x32_bf16 v[98:101], v[184:187], v[202:205], v[98:101]
	v_mfma_f32_16x16x32_bf16 v[86:89], v[176:179], v[210:213], v[86:89]
	v_mfma_f32_16x16x32_bf16 v[82:85], v[184:187], v[210:213], v[82:85]
	v_mfma_f32_16x16x32_bf16 v[70:73], v[176:179], v[218:221], v[70:73]
	v_mfma_f32_16x16x32_bf16 v[66:69], v[184:187], v[218:221], v[66:69]
	v_mfma_f32_16x16x32_bf16 v[118:121], v[180:183], v[198:201], v[118:121]
	v_mfma_f32_16x16x32_bf16 v[114:117], v[188:191], v[198:201], v[114:117]
	v_mfma_f32_16x16x32_bf16 v[102:105], v[180:183], v[206:209], v[102:105]
	v_mfma_f32_16x16x32_bf16 v[98:101], v[188:191], v[206:209], v[98:101]
	v_mfma_f32_16x16x32_bf16 v[86:89], v[180:183], v[214:217], v[86:89]
	v_mfma_f32_16x16x32_bf16 v[82:85], v[188:191], v[214:217], v[82:85]
	v_mfma_f32_16x16x32_bf16 v[70:73], v[180:183], v[222:225], v[70:73]
	v_mfma_f32_16x16x32_bf16 v[66:69], v[188:191], v[222:225], v[66:69]
	s_setprio 0
	s_barrier
	s_add_i32 s77, s69, s56
	v_lshl_add_u64 v[226:227], s[50:51], 0, v[132:133]
	s_mov_b32 m0, s77
	ds_read_b128 v[192:195], v162 offset:16384
	ds_read_b128 v[198:201], v162 offset:17408
	ds_read_b128 v[202:205], v162 offset:18432
	ds_read_b128 v[206:209], v162 offset:19456
	ds_read_b128 v[210:213], v162 offset:20480
	ds_read_b128 v[214:217], v162 offset:21504
	ds_read_b128 v[218:221], v162 offset:22528
	ds_read_b128 v[222:225], v162 offset:23552
	global_load_lds_dwordx4 v[226:227], off
	s_add_i32 m0, s77, 0x2000
	s_add_u32 s78, s50, 0x100000
	v_lshl_add_u64 v[228:229], s[50:51], 0, v[136:137]
	s_addc_u32 s79, s51, 0
	s_add_i32 s77, s70, s56
	global_load_lds_dwordx4 v[228:229], off
	v_lshl_add_u64 v[230:231], s[78:79], 0, v[132:133]
	s_mov_b32 m0, s77
	v_lshl_add_u64 v[232:233], s[52:53], 0, v[134:135]
	global_load_lds_dwordx4 v[230:231], off
	v_lshl_add_u64 v[230:231], s[78:79], 0, v[136:137]
	s_add_i32 m0, s77, 0x2000
	s_nop 0
	global_load_lds_dwordx4 v[230:231], off
	v_lshl_add_u64 v[230:231], s[52:53], 0, v[130:131]
	s_waitcnt vmcnt(6)
	s_waitcnt lgkmcnt(0)
	s_barrier
; #define PG8_STAGE(bufoff, gbase, voff) do { _Pragma("unroll") for (int _i = 0; _i < 2; ++_i) \
;         __builtin_amdgcn_global_load_lds((const unsigned*)((const char*)(gbase) + (voff)[_i]), (PG8_LAS unsigned*)(lds + (bufoff) + ldsw + _i * 8192), 16, 0, 0); } while (0)
; #define PG8_LDA(dst, b, h) do { _Pragma("unroll") for (int m = 0; m < 4; ++m) _Pragma("unroll") for (int k = 0; k < 2; ++k) dst[m][k] = *(const PG8_LAS bf16x8*)(lds + PG8_SA(b, h) + aoff + m * 2048 + k * 1024); } while (0)
; #define PG8_LDB(dst, b, h) do { _Pragma("unroll") for (int n = 0; n < 2; ++n) _Pragma("unroll") for (int k = 0; k < 2; ++k) dst[n][k] = *(const PG8_LAS bf16x8*)(lds + PG8_SB(b, h) + boff + n * 2048 + k * 1024); } while (0)
; #define PG8_MMA(ai, bj, At, Bt) do { __builtin_amdgcn_s_setprio(1); _Pragma("unroll") for (int m = 0; m < 4; ++m) _Pragma("unroll") for (int n = 0; n < 2; ++n) _Pragma("unroll") for (int k = 0; k < 2; ++k) \
;         acc[ai][bj][m][n] = __builtin_amdgcn_mfma_f32_16x16x32_bf16(Bt[n][k], At[m][k], acc[ai][bj][m][n], 0, 0, 0); __builtin_amdgcn_s_setprio(0); } while (0)
; #define PG8_WAIT_V(n) asm volatile("s_waitcnt vmcnt(" #n ")" ::: "memory")
; #define PG8_WAIT_L(n) asm volatile("s_waitcnt lgkmcnt(" #n ")" ::: "memory")
; #define PG8_BAR __builtin_amdgcn_s_barrier()
; #define PG8_SCHED __builtin_amdgcn_sched_barrier(0)
; template <class Epi, class Sched, bool ALIGN_EPI = false, bool SP2 = false>
; __device__ __forceinline__ void gemm_phase(PG8_LAS unsigned char* lds, const Gemm g, const Sched& S, const Epi& E) {
;     ...
;             PG8_LDA(At, 0, 1); PG8_STAGE(PG8_SB(0, 0), b2, voffB); PG8_STAGE(PG8_SB(0, 1), b2 + hstep, voffB); PG8_STAGE(PG8_SA(0, 0), a2, voffA);
;             PG8_WAIT_V(8); PG8_WAIT_L(0); PG8_BAR; PG8_MMA(1, 0, At, B0); PG8_MMA(1, 1, At, B1); PG8_BAR; PG8_SCHED;
;             PG8_LDB(B0, 1, 0); PG8_LDB(B1, 1, 1); PG8_SCHED; PG8_LDA(At, 1, 0); PG8_STAGE(PG8_SA(0, 1), a2 + hstep, voffA);
	s_setprio 1
	s_waitcnt lgkmcnt(0)
	v_mfma_f32_16x16x32_bf16 v[62:65], v[146:149], v[192:195], v[62:65]
	v_mfma_f32_16x16x32_bf16 v[58:61], v[168:171], v[192:195], v[58:61]
	v_mfma_f32_16x16x32_bf16 v[46:49], v[146:149], v[202:205], v[46:49]
	v_mfma_f32_16x16x32_bf16 v[42:45], v[168:171], v[202:205], v[42:45]
	v_mfma_f32_16x16x32_bf16 v[30:33], v[146:149], v[210:213], v[30:33]
	v_mfma_f32_16x16x32_bf16 v[26:29], v[168:171], v[210:213], v[26:29]
	v_mfma_f32_16x16x32_bf16 v[14:17], v[146:149], v[218:221], v[14:17]
	v_mfma_f32_16x16x32_bf16 v[10:13], v[168:171], v[218:221], v[10:13]
	v_mfma_f32_16x16x32_bf16 v[62:65], v[164:167], v[198:201], v[62:65]
	v_mfma_f32_16x16x32_bf16 v[58:61], v[172:175], v[198:201], v[58:61]
	v_mfma_f32_16x16x32_bf16 v[46:49], v[164:167], v[206:209], v[46:49]
	v_mfma_f32_16x16x32_bf16 v[42:45], v[172:175], v[206:209], v[42:45]
	v_mfma_f32_16x16x32_bf16 v[30:33], v[164:167], v[214:217], v[30:33]
	v_mfma_f32_16x16x32_bf16 v[26:29], v[172:175], v[214:217], v[26:29]
	v_mfma_f32_16x16x32_bf16 v[14:17], v[164:167], v[222:225], v[14:17]
	v_mfma_f32_16x16x32_bf16 v[10:13], v[172:175], v[222:225], v[10:13]
	s_setprio 0
	s_setprio 1
	v_mfma_f32_16x16x32_bf16 v[54:57], v[176:179], v[192:195], v[54:57]
	v_mfma_f32_16x16x32_bf16 v[50:53], v[184:187], v[192:195], v[50:53]
	v_mfma_f32_16x16x32_bf16 v[38:41], v[176:179], v[202:205], v[38:41]
	v_mfma_f32_16x16x32_bf16 v[34:37], v[184:187], v[202:205], v[34:37]
	v_mfma_f32_16x16x32_bf16 v[22:25], v[176:179], v[210:213], v[22:25]
	v_mfma_f32_16x16x32_bf16 v[18:21], v[184:187], v[210:213], v[18:21]
	v_mfma_f32_16x16x32_bf16 v[6:9], v[176:179], v[218:221], v[6:9]
	v_mfma_f32_16x16x32_bf16 v[2:5], v[184:187], v[218:221], v[2:5]
	v_mfma_f32_16x16x32_bf16 v[54:57], v[180:183], v[198:201], v[54:57]
	v_mfma_f32_16x16x32_bf16 v[50:53], v[188:191], v[198:201], v[50:53]
	v_mfma_f32_16x16x32_bf16 v[38:41], v[180:183], v[206:209], v[38:41]
	v_mfma_f32_16x16x32_bf16 v[34:37], v[188:191], v[206:209], v[34:37]
	v_mfma_f32_16x16x32_bf16 v[22:25], v[180:183], v[214:217], v[22:25]
	v_mfma_f32_16x16x32_bf16 v[18:21], v[188:191], v[214:217], v[18:21]
	v_mfma_f32_16x16x32_bf16 v[6:9], v[180:183], v[222:225], v[6:9]
	v_mfma_f32_16x16x32_bf16 v[2:5], v[188:191], v[222:225], v[2:5]
	s_setprio 0
	s_barrier
	s_add_i32 s77, 0, 0x18000
	s_add_i32 s78, 0, 0x1c000
	v_add_u32_e32 v172, s77, v151
	v_add_u32_e32 v188, s78, v151
	ds_read_b128 v[146:149], v172
	ds_read_b128 v[164:167], v172 offset:1024
	ds_read_b128 v[168:171], v172 offset:2048
	ds_read_b128 v[172:175], v172 offset:3072
	ds_read_b128 v[176:179], v188
	ds_read_b128 v[180:183], v188 offset:1024
	ds_read_b128 v[184:187], v188 offset:2048
	ds_read_b128 v[188:191], v188 offset:3072
	s_add_u32 s52, s52, 0x100000
	s_addc_u32 s53, s53, 0
	s_mov_b32 m0, s9
	s_nop 0
	global_load_lds_dwordx4 v[230:231], off
	s_mov_b32 m0, s57
	s_nop 0
	global_load_lds_dwordx4 v[232:233], off
	s_mov_b32 m0, s58
	v_lshl_add_u64 v[234:235], s[52:53], 0, v[130:131]
	ds_read_b128 v[192:195], v162 offset:32768
	ds_read_b128 v[198:201], v162 offset:33792
	ds_read_b128 v[202:205], v162 offset:34816
	ds_read_b128 v[206:209], v162 offset:35840
	ds_read_b128 v[210:213], v162 offset:36864
	ds_read_b128 v[214:217], v162 offset:37888
	ds_read_b128 v[218:221], v162 offset:38912
	ds_read_b128 v[222:225], v162 offset:39936
	global_load_lds_dwordx4 v[234:235], off
	v_lshl_add_u64 v[234:235], s[52:53], 0, v[134:135]
	s_mov_b32 m0, s59
	s_nop 0
	global_load_lds_dwordx4 v[234:235], off
	s_waitcnt vmcnt(8)
	s_waitcnt lgkmcnt(0)
	s_barrier
; #define PG8_STAGE(bufoff, gbase, voff) do { _Pragma("unroll") for (int _i = 0; _i < 2; ++_i) \
;         __builtin_amdgcn_global_load_lds((const unsigned*)((const char*)(gbase) + (voff)[_i]), (PG8_LAS unsigned*)(lds + (bufoff) + ldsw + _i * 8192), 16, 0, 0); } while (0)
; #define PG8_LDA(dst, b, h) do { _Pragma("unroll") for (int m = 0; m < 4; ++m) _Pragma("unroll") for (int k = 0; k < 2; ++k) dst[m][k] = *(const PG8_LAS bf16x8*)(lds + PG8_SA(b, h) + aoff + m * 2048 + k * 1024); } while (0)
; #define PG8_LDB(dst, b, h) do { _Pragma("unroll") for (int n = 0; n < 2; ++n) _Pragma("unroll") for (int k = 0; k < 2; ++k) dst[n][k] = *(const PG8_LAS bf16x8*)(lds + PG8_SB(b, h) + boff + n * 2048 + k * 1024); } while (0)
; #define PG8_MMA(ai, bj, At, Bt) do { __builtin_amdgcn_s_setprio(1); _Pragma("unroll") for (int m = 0; m < 4; ++m) _Pragma("unroll") for (int n = 0; n < 2; ++n) _Pragma("unroll") for (int k = 0; k < 2; ++k) \
;         acc[ai][bj][m][n] = __builtin_amdgcn_mfma_f32_16x16x32_bf16(Bt[n][k], At[m][k], acc[ai][bj][m][n], 0, 0, 0); __builtin_amdgcn_s_setprio(0); } while (0)
; #define PG8_WAIT_V(n) asm volatile("s_waitcnt vmcnt(" #n ")" ::: "memory")
; #define PG8_WAIT_L(n) asm volatile("s_waitcnt lgkmcnt(" #n ")" ::: "memory")
; #define PG8_BAR __builtin_amdgcn_s_barrier()
; #define PG8_SCHED __builtin_amdgcn_sched_barrier(0)
; template <class Epi, class Sched, bool ALIGN_EPI = false, bool SP2 = false>
; __device__ __forceinline__ void gemm_phase(PG8_LAS unsigned char* lds, const Gemm g, const Sched& S, const Epi& E) {
;     ...
;             PG8_LDB(B0, 1, 0); PG8_LDB(B1, 1, 1); PG8_SCHED; PG8_LDA(At, 1, 0); PG8_STAGE(PG8_SA(0, 1), a2 + hstep, voffA);
;             PG8_WAIT_V(8); PG8_WAIT_L(0); PG8_BAR; PG8_MMA(0, 0, At, B0); PG8_MMA(0, 1, At, B1); PG8_BAR; PG8_SCHED;
;             PG8_LDA(At, 1, 1); PG8_STAGE(PG8_SB(1, 0), b3, voffB); PG8_STAGE(PG8_SB(1, 1), b3 + hstep, voffB); PG8_STAGE(PG8_SA(1, 0), a3, voffA);
;             PG8_WAIT_V(8); PG8_WAIT_L(0); PG8_BAR; PG8_MMA(1, 0, At, B0); PG8_MMA(1, 1, At, B1); PG8_BAR; PG8_SCHED;
	s_setprio 1
	s_waitcnt lgkmcnt(0)
	v_mfma_f32_16x16x32_bf16 v[126:129], v[146:149], v[192:195], v[126:129]
	v_mfma_f32_16x16x32_bf16 v[122:125], v[168:171], v[192:195], v[122:125]
	v_mfma_f32_16x16x32_bf16 v[110:113], v[146:149], v[202:205], v[110:113]
	v_mfma_f32_16x16x32_bf16 v[106:109], v[168:171], v[202:205], v[106:109]
	v_mfma_f32_16x16x32_bf16 v[94:97], v[146:149], v[210:213], v[94:97]
	v_mfma_f32_16x16x32_bf16 v[90:93], v[168:171], v[210:213], v[90:93]
	v_mfma_f32_16x16x32_bf16 v[78:81], v[146:149], v[218:221], v[78:81]
	v_mfma_f32_16x16x32_bf16 v[74:77], v[168:171], v[218:221], v[74:77]
	v_mfma_f32_16x16x32_bf16 v[126:129], v[164:167], v[198:201], v[126:129]
	v_mfma_f32_16x16x32_bf16 v[122:125], v[172:175], v[198:201], v[122:125]
	v_mfma_f32_16x16x32_bf16 v[110:113], v[164:167], v[206:209], v[110:113]
	v_mfma_f32_16x16x32_bf16 v[106:109], v[172:175], v[206:209], v[106:109]
	v_mfma_f32_16x16x32_bf16 v[94:97], v[164:167], v[214:217], v[94:97]
	v_mfma_f32_16x16x32_bf16 v[90:93], v[172:175], v[214:217], v[90:93]
	v_mfma_f32_16x16x32_bf16 v[78:81], v[164:167], v[222:225], v[78:81]
	v_mfma_f32_16x16x32_bf16 v[74:77], v[172:175], v[222:225], v[74:77]
	s_setprio 0
	s_setprio 1
	v_mfma_f32_16x16x32_bf16 v[118:121], v[176:179], v[192:195], v[118:121]
	v_mfma_f32_16x16x32_bf16 v[114:117], v[184:187], v[192:195], v[114:117]
	v_mfma_f32_16x16x32_bf16 v[102:105], v[176:179], v[202:205], v[102:105]
	v_mfma_f32_16x16x32_bf16 v[98:101], v[184:187], v[202:205], v[98:101]
	v_mfma_f32_16x16x32_bf16 v[86:89], v[176:179], v[210:213], v[86:89]
	v_mfma_f32_16x16x32_bf16 v[82:85], v[184:187], v[210:213], v[82:85]
	v_mfma_f32_16x16x32_bf16 v[70:73], v[176:179], v[218:221], v[70:73]
	v_mfma_f32_16x16x32_bf16 v[66:69], v[184:187], v[218:221], v[66:69]
	v_mfma_f32_16x16x32_bf16 v[118:121], v[180:183], v[198:201], v[118:121]
	v_mfma_f32_16x16x32_bf16 v[114:117], v[188:191], v[198:201], v[114:117]
	v_mfma_f32_16x16x32_bf16 v[102:105], v[180:183], v[206:209], v[102:105]
	v_mfma_f32_16x16x32_bf16 v[98:101], v[188:191], v[206:209], v[98:101]
	v_mfma_f32_16x16x32_bf16 v[86:89], v[180:183], v[214:217], v[86:89]
	v_mfma_f32_16x16x32_bf16 v[82:85], v[188:191], v[214:217], v[82:85]
	v_mfma_f32_16x16x32_bf16 v[70:73], v[180:183], v[222:225], v[70:73]
	v_mfma_f32_16x16x32_bf16 v[66:69], v[188:191], v[222:225], v[66:69]
	s_setprio 0
	s_barrier
	s_add_i32 s52, s77, s56
	v_lshl_add_u64 v[226:227], v[226:227], 0, s[36:37]
	s_mov_b32 m0, s52
	ds_read_b128 v[192:195], v162 offset:49152
	ds_read_b128 v[198:201], v162 offset:50176
	ds_read_b128 v[202:205], v162 offset:51200
	ds_read_b128 v[206:209], v162 offset:52224
	ds_read_b128 v[210:213], v162 offset:53248
	ds_read_b128 v[214:217], v162 offset:54272
	ds_read_b128 v[218:221], v162 offset:55296
	ds_read_b128 v[222:225], v162 offset:56320
	global_load_lds_dwordx4 v[226:227], off
	s_add_i32 m0, s52, 0x2000
	s_add_u32 s50, s50, 0x100080
	v_lshl_add_u64 v[226:227], v[228:229], 0, s[36:37]
	s_addc_u32 s51, s51, 0
	s_add_i32 s52, s78, s56
	global_load_lds_dwordx4 v[226:227], off
	v_lshl_add_u64 v[226:227], s[50:51], 0, v[132:133]
	s_mov_b32 m0, s52
	s_nop 0
	global_load_lds_dwordx4 v[226:227], off
	v_lshl_add_u64 v[226:227], s[50:51], 0, v[136:137]
	s_add_i32 m0, s52, 0x2000
	s_nop 0
	global_load_lds_dwordx4 v[226:227], off
	s_waitcnt vmcnt(6)
	s_waitcnt lgkmcnt(0)
	s_barrier
	s_setprio 1
	s_waitcnt lgkmcnt(0)
	v_mfma_f32_16x16x32_bf16 v[62:65], v[146:149], v[192:195], v[62:65]
	v_mfma_f32_16x16x32_bf16 v[58:61], v[168:171], v[192:195], v[58:61]
	v_mfma_f32_16x16x32_bf16 v[46:49], v[146:149], v[202:205], v[46:49]
	v_mfma_f32_16x16x32_bf16 v[42:45], v[168:171], v[202:205], v[42:45]
	v_mfma_f32_16x16x32_bf16 v[30:33], v[146:149], v[210:213], v[30:33]
	v_mfma_f32_16x16x32_bf16 v[26:29], v[168:171], v[210:213], v[26:29]
	v_mfma_f32_16x16x32_bf16 v[14:17], v[146:149], v[218:221], v[14:17]
	v_mfma_f32_16x16x32_bf16 v[10:13], v[168:171], v[218:221], v[10:13]
	v_mfma_f32_16x16x32_bf16 v[62:65], v[164:167], v[198:201], v[62:65]
	v_mfma_f32_16x16x32_bf16 v[58:61], v[172:175], v[198:201], v[58:61]
	v_mfma_f32_16x16x32_bf16 v[46:49], v[164:167], v[206:209], v[46:49]
	v_mfma_f32_16x16x32_bf16 v[42:45], v[172:175], v[206:209], v[42:45]
	v_mfma_f32_16x16x32_bf16 v[30:33], v[164:167], v[214:217], v[30:33]
	v_mfma_f32_16x16x32_bf16 v[26:29], v[172:175], v[214:217], v[26:29]
	v_mfma_f32_16x16x32_bf16 v[14:17], v[164:167], v[222:225], v[14:17]
	v_mfma_f32_16x16x32_bf16 v[10:13], v[172:175], v[222:225], v[10:13]
	s_setprio 0
	s_setprio 1
	v_mfma_f32_16x16x32_bf16 v[54:57], v[176:179], v[192:195], v[54:57]
	v_mfma_f32_16x16x32_bf16 v[50:53], v[184:187], v[192:195], v[50:53]
	v_mfma_f32_16x16x32_bf16 v[38:41], v[176:179], v[202:205], v[38:41]
	v_mfma_f32_16x16x32_bf16 v[34:37], v[184:187], v[202:205], v[34:37]
	v_mfma_f32_16x16x32_bf16 v[22:25], v[176:179], v[210:213], v[22:25]
	v_mfma_f32_16x16x32_bf16 v[18:21], v[184:187], v[210:213], v[18:21]
	v_mfma_f32_16x16x32_bf16 v[6:9], v[176:179], v[218:221], v[6:9]
	v_mfma_f32_16x16x32_bf16 v[2:5], v[184:187], v[218:221], v[2:5]
	v_mfma_f32_16x16x32_bf16 v[54:57], v[180:183], v[198:201], v[54:57]
	v_mfma_f32_16x16x32_bf16 v[50:53], v[188:191], v[198:201], v[50:53]
	v_mfma_f32_16x16x32_bf16 v[38:41], v[180:183], v[206:209], v[38:41]
	v_mfma_f32_16x16x32_bf16 v[34:37], v[188:191], v[206:209], v[34:37]
	v_mfma_f32_16x16x32_bf16 v[22:25], v[180:183], v[214:217], v[22:25]
	v_mfma_f32_16x16x32_bf16 v[18:21], v[188:191], v[214:217], v[18:21]
	v_mfma_f32_16x16x32_bf16 v[6:9], v[180:183], v[222:225], v[6:9]
	v_mfma_f32_16x16x32_bf16 v[2:5], v[188:191], v[222:225], v[2:5]
	s_setprio 0
	s_barrier
	s_add_i32 s76, s76, 2
	s_add_u32 s48, s48, 0x100
	s_addc_u32 s49, s49, 0
	s_add_u32 s74, s74, 0x100
	s_addc_u32 s75, s75, 0
	s_cmp_gt_u32 s76, 61
	s_cbranch_scc0 .LBB0_710
	s_and_b64 vcc, exec, s[38:39]
	s_cbranch_vccz .LBB0_713
	s_barrier

; #define PG8_STAGE(bufoff, gbase, voff) do { _Pragma("unroll") for (int _i = 0; _i < 2; ++_i) \
;         __builtin_amdgcn_global_load_lds((const unsigned*)((const char*)(gbase) + (voff)[_i]), (PG8_LAS unsigned*)(lds + (bufoff) + ldsw + _i * 8192), 16, 0, 0); } while (0)
; #define PG8_WAIT_V(n) asm volatile("s_waitcnt vmcnt(" #n ")" ::: "memory")
; #define PG8_BAR __builtin_amdgcn_s_barrier()
; template <class Epi, class Sched, bool ALIGN_EPI = false, bool SP2 = false>
; __device__ __forceinline__ void gemm_phase(PG8_LAS unsigned char* lds, const Gemm g, const Sched& S, const Epi& E) {
;     ...
;     const unsigned ldsw = (unsigned)wid * 1024u;
;     const int aoff = lds_byte(wr * 64 + fr, fq * 8), boff = lds_byte(wc * 32 + fr, fq * 8);
;     ...
;         PG8_STAGE(PG8_SB(1, 0), cB + kstep, voffB); PG8_STAGE(PG8_SA(1, 0), cA + kstep, voffA); PG8_STAGE(PG8_SB(1, 1), cB + hstep + kstep, voffB);
;         PG8_WAIT_V(6); PG8_BAR;
.LBB0_875:
	s_add_u32 s8, s2, 0x1d200000
	s_addc_u32 s9, s3, 0
	s_add_u32 s10, s2, 0x18710000
	s_addc_u32 s11, s3, 0
	s_lshl_b32 s2, s12, 5
	s_mov_b64 s[12:13], 0x80
	s_and_b32 s36, s2, 0x60
	s_add_i32 m0, s43, 0x18000
	v_lshl_add_u64 v[8:9], v[8:9], 0, s[12:13]
	s_lshl_b32 s35, s34, 13
	s_lshl_b32 s37, s36, 7
	s_waitcnt vmcnt(2)
	s_barrier
	global_load_lds_dwordx4 v[8:9], off
	v_lshl_add_u64 v[6:7], v[6:7], 0, s[12:13]
	s_add_i32 m0, s43, 0x1a000
	s_add_i32 s59, s43, 0x8000
	s_add_i32 s60, s43, 0xa000
	global_load_lds_dwordx4 v[6:7], off
	v_mov_b32_e32 v224, v2
	v_mov_b32_e32 v225, v3
	v_lshl_add_u64 v[2:3], v[2:3], 0, s[12:13]
	s_mov_b32 m0, s59
	s_add_u32 s2, s46, 0x100080
	global_load_lds_dwordx4 v[2:3], off
	v_mov_b32_e32 v226, v4
	v_mov_b32_e32 v227, v5
	v_lshl_add_u64 v[2:3], v[4:5], 0, s[12:13]
	s_mov_b32 m0, s60
	s_addc_u32 s3, s47, 0
	global_load_lds_dwordx4 v[2:3], off
	s_add_i32 m0, s43, 0x1c000
	v_lshl_add_u64 v[2:3], s[2:3], 0, v[134:135]
	global_load_lds_dwordx4 v[2:3], off
	v_lshl_add_u64 v[2:3], s[2:3], 0, v[130:131]
	s_add_i32 m0, s43, 0x1e000
	v_lshlrev_b32_e32 v5, 6, v1
	global_load_lds_dwordx4 v[2:3], off
	v_and_b32_e32 v2, 15, v1
	v_lshlrev_b32_e32 v3, 1, v13
	s_movk_i32 s2, 0x3c0
	v_lshl_or_b32 v149, s34, 6, v2
	v_lshl_or_b32 v2, v2, 6, v3
	v_and_b32_e32 v4, 32, v148
	v_and_or_b32 v3, v5, s2, v3
	v_bitop3_b32 v150, s37, v3, v4 bitop3:0xf6
	v_lshlrev_b32_e32 v3, 10, v1
	v_bitop3_b32 v2, v2, s35, v4 bitop3:0xde
	v_and_b32_e32 v3, 0xe0000, v3
	v_lshlrev_b32_e32 v4, 13, v14
	v_or3_b32 v3, v11, v3, v4
	v_add_u32_e32 v138, v3, v12
	v_lshlrev_b32_e32 v3, 6, v10
	s_waitcnt vmcnt(6)
	s_cmpk_lt_u32 s17, 0x100
	v_and_b32_e32 v3, 0x1e0000, v3
	s_sext_i32_i16 s69, s16
	s_cselect_b64 s[16:17], -1, 0
	v_or3_b32 v3, v11, v3, v4
	s_add_i32 s63, 0, 0x10000
	s_add_i32 s67, 0, 0x14000
	s_ashr_i32 s61, s22, 31
	s_mov_b32 s62, s22
	v_or_b32_e32 v151, s36, v13
	v_mov_b32_e32 v139, v135
	v_add_u32_e32 v140, v3, v12
	v_mov_b32_e32 v141, v135
	v_mov_b64_e32 v[142:143], 0xac0
	v_mov_b64_e32 v[144:145], 0xabf
	v_add_u32_e32 v152, s63, v150
	v_add_u32_e32 v153, s67, v150
	v_add_u32_e32 v154, 0, v2
	s_movk_i32 s68, 0x5600
	s_barrier
	s_branch .LBB0_878

; #define PG8_STAGE(bufoff, gbase, voff) do { _Pragma("unroll") for (int _i = 0; _i < 2; ++_i) \
;         __builtin_amdgcn_global_load_lds((const unsigned*)((const char*)(gbase) + (voff)[_i]), (PG8_LAS unsigned*)(lds + (bufoff) + ldsw + _i * 8192), 16, 0, 0); } while (0)
; #define PG8_LDA(dst, b, h) do { _Pragma("unroll") for (int m = 0; m < 4; ++m) _Pragma("unroll") for (int k = 0; k < 2; ++k) dst[m][k] = *(const PG8_LAS bf16x8*)(lds + PG8_SA(b, h) + aoff + m * 2048 + k * 1024); } while (0)
; #define PG8_LDB(dst, b, h) do { _Pragma("unroll") for (int n = 0; n < 2; ++n) _Pragma("unroll") for (int k = 0; k < 2; ++k) dst[n][k] = *(const PG8_LAS bf16x8*)(lds + PG8_SB(b, h) + boff + n * 2048 + k * 1024); } while (0)
; #define PG8_MMA(ai, bj, At, Bt) do { __builtin_amdgcn_s_setprio(1); _Pragma("unroll") for (int m = 0; m < 4; ++m) _Pragma("unroll") for (int n = 0; n < 2; ++n) _Pragma("unroll") for (int k = 0; k < 2; ++k) \
;         acc[ai][bj][m][n] = __builtin_amdgcn_mfma_f32_16x16x32_bf16(Bt[n][k], At[m][k], acc[ai][bj][m][n], 0, 0, 0); __builtin_amdgcn_s_setprio(0); } while (0)
; #define PG8_WAIT_V(n) asm volatile("s_waitcnt vmcnt(" #n ")" ::: "memory")
; #define PG8_WAIT_L(n) asm volatile("s_waitcnt lgkmcnt(" #n ")" ::: "memory")
; #define PG8_BAR __builtin_amdgcn_s_barrier()
; #define PG8_SCHED __builtin_amdgcn_sched_barrier(0)
; template <class Epi, class Sched, bool ALIGN_EPI = false, bool SP2 = false>
; __device__ __forceinline__ void gemm_phase(PG8_LAS unsigned char* lds, const Gemm g, const Sched& S, const Epi& E) {
;     ...
;             PG8_LDB(B0, 0, 0); PG8_LDB(B1, 0, 1); PG8_SCHED; PG8_LDA(At, 0, 0); PG8_STAGE(PG8_SA(1, 1), a1 + hstep, voffA);
;             PG8_WAIT_V(8); PG8_WAIT_L(0); PG8_BAR; PG8_MMA(0, 0, At, B0); PG8_MMA(0, 1, At, B1); PG8_BAR; PG8_SCHED;
;             PG8_LDA(At, 0, 1); PG8_STAGE(PG8_SB(0, 0), b2, voffB); PG8_STAGE(PG8_SB(0, 1), b2 + hstep, voffB); PG8_STAGE(PG8_SA(0, 0), a2, voffA);
.LBB0_881:
	ds_read_b128 v[156:159], v152
	ds_read_b128 v[160:163], v152 offset:1024
	ds_read_b128 v[164:167], v152 offset:2048
	ds_read_b128 v[168:171], v152 offset:3072
	ds_read_b128 v[172:175], v153
	ds_read_b128 v[176:179], v153 offset:1024
	ds_read_b128 v[180:183], v153 offset:2048
	ds_read_b128 v[184:187], v153 offset:3072
	s_add_u32 s46, s44, 0xfff00080
	s_addc_u32 s47, s45, -1
	s_cmp_eq_u32 s74, 60
	s_cselect_b32 s49, s37, s47
	s_cselect_b32 s48, s70, s46
	s_cselect_b32 s47, s35, s73
	s_cselect_b32 s46, s71, s72
	v_lshl_add_u64 v[146:147], v[224:225], 0, s[12:13]
	s_mov_b32 m0, s59
	s_nop 0
	global_load_lds_dwordx4 v[146:147], off
	v_lshl_add_u64 v[146:147], v[226:227], 0, s[12:13]
	s_mov_b32 m0, s60
	s_nop 0
	global_load_lds_dwordx4 v[146:147], off
	v_lshl_add_u64 v[146:147], s[44:45], 0, v[138:139]
	s_add_i32 m0, s43, 0xc000
	ds_read_b128 v[188:191], v154
	ds_read_b128 v[192:195], v154 offset:1024
	ds_read_b128 v[198:201], v154 offset:2048
	ds_read_b128 v[202:205], v154 offset:3072
	ds_read_b128 v[206:209], v154 offset:4096
	ds_read_b128 v[210:213], v154 offset:5120
	ds_read_b128 v[214:217], v154 offset:6144
	ds_read_b128 v[218:221], v154 offset:7168
	global_load_lds_dwordx4 v[146:147], off
	v_lshl_add_u64 v[146:147], s[44:45], 0, v[140:141]
	s_add_i32 m0, s43, 0xe000
	s_nop 0
	global_load_lds_dwordx4 v[146:147], off
	s_waitcnt vmcnt(8)
	s_waitcnt lgkmcnt(0)
	s_barrier
	s_setprio 1
	s_waitcnt lgkmcnt(0)
	v_mfma_f32_16x16x32_bf16 v[122:125], v[156:159], v[188:191], v[122:125]
	v_mfma_f32_16x16x32_bf16 v[114:117], v[164:167], v[188:191], v[114:117]
	v_mfma_f32_16x16x32_bf16 v[106:109], v[156:159], v[198:201], v[106:109]
	v_mfma_f32_16x16x32_bf16 v[98:101], v[164:167], v[198:201], v[98:101]
	v_mfma_f32_16x16x32_bf16 v[90:93], v[156:159], v[206:209], v[90:93]
	v_mfma_f32_16x16x32_bf16 v[82:85], v[164:167], v[206:209], v[82:85]
	v_mfma_f32_16x16x32_bf16 v[74:77], v[156:159], v[214:217], v[74:77]
	v_mfma_f32_16x16x32_bf16 v[66:69], v[164:167], v[214:217], v[66:69]
	v_mfma_f32_16x16x32_bf16 v[122:125], v[160:163], v[192:195], v[122:125]
	v_mfma_f32_16x16x32_bf16 v[114:117], v[168:171], v[192:195], v[114:117]
	v_mfma_f32_16x16x32_bf16 v[106:109], v[160:163], v[202:205], v[106:109]
	v_mfma_f32_16x16x32_bf16 v[98:101], v[168:171], v[202:205], v[98:101]
	v_mfma_f32_16x16x32_bf16 v[90:93], v[160:163], v[210:213], v[90:93]
	v_mfma_f32_16x16x32_bf16 v[82:85], v[168:171], v[210:213], v[82:85]
	v_mfma_f32_16x16x32_bf16 v[74:77], v[160:163], v[218:221], v[74:77]
	v_mfma_f32_16x16x32_bf16 v[66:69], v[168:171], v[218:221], v[66:69]
	s_setprio 0
	s_setprio 1
	v_mfma_f32_16x16x32_bf16 v[126:129], v[172:175], v[188:191], v[126:129]
	v_mfma_f32_16x16x32_bf16 v[118:121], v[180:183], v[188:191], v[118:121]
	v_mfma_f32_16x16x32_bf16 v[110:113], v[172:175], v[198:201], v[110:113]
	v_mfma_f32_16x16x32_bf16 v[102:105], v[180:183], v[198:201], v[102:105]
	v_mfma_f32_16x16x32_bf16 v[94:97], v[172:175], v[206:209], v[94:97]
	v_mfma_f32_16x16x32_bf16 v[86:89], v[180:183], v[206:209], v[86:89]
	v_mfma_f32_16x16x32_bf16 v[78:81], v[172:175], v[214:217], v[78:81]
	v_mfma_f32_16x16x32_bf16 v[70:73], v[180:183], v[214:217], v[70:73]
	v_mfma_f32_16x16x32_bf16 v[126:129], v[176:179], v[192:195], v[126:129]
	v_mfma_f32_16x16x32_bf16 v[118:121], v[184:187], v[192:195], v[118:121]
	v_mfma_f32_16x16x32_bf16 v[110:113], v[176:179], v[202:205], v[110:113]
	v_mfma_f32_16x16x32_bf16 v[102:105], v[184:187], v[202:205], v[102:105]
	v_mfma_f32_16x16x32_bf16 v[94:97], v[176:179], v[210:213], v[94:97]
	v_mfma_f32_16x16x32_bf16 v[86:89], v[184:187], v[210:213], v[86:89]
	v_mfma_f32_16x16x32_bf16 v[78:81], v[176:179], v[218:221], v[78:81]
	v_mfma_f32_16x16x32_bf16 v[70:73], v[184:187], v[218:221], v[70:73]
	s_setprio 0
	s_barrier
	s_add_i32 s75, s63, s52
	v_lshl_add_u64 v[146:147], s[46:47], 0, v[134:135]
	s_mov_b32 m0, s75
	ds_read_b128 v[188:191], v154 offset:16384
	ds_read_b128 v[192:195], v154 offset:17408
	ds_read_b128 v[198:201], v154 offset:18432
	ds_read_b128 v[202:205], v154 offset:19456
	ds_read_b128 v[206:209], v154 offset:20480
	ds_read_b128 v[210:213], v154 offset:21504
	ds_read_b128 v[214:217], v154 offset:22528
	ds_read_b128 v[218:221], v154 offset:23552
	global_load_lds_dwordx4 v[146:147], off
	s_add_i32 m0, s75, 0x2000
	s_add_u32 s76, s46, 0x100000
	v_lshl_add_u64 v[222:223], s[46:47], 0, v[130:131]
	s_addc_u32 s77, s47, 0
	s_add_i32 s75, s67, s52
	global_load_lds_dwordx4 v[222:223], off
	v_lshl_add_u64 v[224:225], s[76:77], 0, v[134:135]
	s_mov_b32 m0, s75
	v_lshl_add_u64 v[226:227], s[48:49], 0, v[132:133]
	global_load_lds_dwordx4 v[224:225], off
	v_lshl_add_u64 v[224:225], s[76:77], 0, v[130:131]
	s_add_i32 m0, s75, 0x2000
	s_nop 0
	global_load_lds_dwordx4 v[224:225], off
	v_lshl_add_u64 v[224:225], s[48:49], 0, v[136:137]
	s_waitcnt vmcnt(6)
	s_waitcnt lgkmcnt(0)
	s_barrier
; #define PG8_STAGE(bufoff, gbase, voff) do { _Pragma("unroll") for (int _i = 0; _i < 2; ++_i) \
;         __builtin_amdgcn_global_load_lds((const unsigned*)((const char*)(gbase) + (voff)[_i]), (PG8_LAS unsigned*)(lds + (bufoff) + ldsw + _i * 8192), 16, 0, 0); } while (0)
; #define PG8_LDA(dst, b, h) do { _Pragma("unroll") for (int m = 0; m < 4; ++m) _Pragma("unroll") for (int k = 0; k < 2; ++k) dst[m][k] = *(const PG8_LAS bf16x8*)(lds + PG8_SA(b, h) + aoff + m * 2048 + k * 1024); } while (0)
; #define PG8_LDB(dst, b, h) do { _Pragma("unroll") for (int n = 0; n < 2; ++n) _Pragma("unroll") for (int k = 0; k < 2; ++k) dst[n][k] = *(const PG8_LAS bf16x8*)(lds + PG8_SB(b, h) + boff + n * 2048 + k * 1024); } while (0)
; #define PG8_MMA(ai, bj, At, Bt) do { __builtin_amdgcn_s_setprio(1); _Pragma("unroll") for (int m = 0; m < 4; ++m) _Pragma("unroll") for (int n = 0; n < 2; ++n) _Pragma("unroll") for (int k = 0; k < 2; ++k) \
;         acc[ai][bj][m][n] = __builtin_amdgcn_mfma_f32_16x16x32_bf16(Bt[n][k], At[m][k], acc[ai][bj][m][n], 0, 0, 0); __builtin_amdgcn_s_setprio(0); } while (0)
; #define PG8_WAIT_V(n) asm volatile("s_waitcnt vmcnt(" #n ")" ::: "memory")
; #define PG8_WAIT_L(n) asm volatile("s_waitcnt lgkmcnt(" #n ")" ::: "memory")
; #define PG8_BAR __builtin_amdgcn_s_barrier()
; #define PG8_SCHED __builtin_amdgcn_sched_barrier(0)
; template <class Epi, class Sched, bool ALIGN_EPI = false, bool SP2 = false>
; __device__ __forceinline__ void gemm_phase(PG8_LAS unsigned char* lds, const Gemm g, const Sched& S, const Epi& E) {
;     ...
;             PG8_LDA(At, 0, 1); PG8_STAGE(PG8_SB(0, 0), b2, voffB); PG8_STAGE(PG8_SB(0, 1), b2 + hstep, voffB); PG8_STAGE(PG8_SA(0, 0), a2, voffA);
;             PG8_WAIT_V(8); PG8_WAIT_L(0); PG8_BAR; PG8_MMA(1, 0, At, B0); PG8_MMA(1, 1, At, B1); PG8_BAR; PG8_SCHED;
;             PG8_LDB(B0, 1, 0); PG8_LDB(B1, 1, 1); PG8_SCHED; PG8_LDA(At, 1, 0); PG8_STAGE(PG8_SA(0, 1), a2 + hstep, voffA);
	s_setprio 1
	s_waitcnt lgkmcnt(0)
	v_mfma_f32_16x16x32_bf16 v[58:61], v[156:159], v[188:191], v[58:61]
	v_mfma_f32_16x16x32_bf16 v[50:53], v[164:167], v[188:191], v[50:53]
	v_mfma_f32_16x16x32_bf16 v[42:45], v[156:159], v[198:201], v[42:45]
	v_mfma_f32_16x16x32_bf16 v[34:37], v[164:167], v[198:201], v[34:37]
	v_mfma_f32_16x16x32_bf16 v[26:29], v[156:159], v[206:209], v[26:29]
	v_mfma_f32_16x16x32_bf16 v[18:21], v[164:167], v[206:209], v[18:21]
	v_mfma_f32_16x16x32_bf16 v[10:13], v[156:159], v[214:217], v[10:13]
	v_mfma_f32_16x16x32_bf16 v[6:9], v[164:167], v[214:217], v[6:9]
	v_mfma_f32_16x16x32_bf16 v[58:61], v[160:163], v[192:195], v[58:61]
	v_mfma_f32_16x16x32_bf16 v[50:53], v[168:171], v[192:195], v[50:53]
	v_mfma_f32_16x16x32_bf16 v[42:45], v[160:163], v[202:205], v[42:45]
	v_mfma_f32_16x16x32_bf16 v[34:37], v[168:171], v[202:205], v[34:37]
	v_mfma_f32_16x16x32_bf16 v[26:29], v[160:163], v[210:213], v[26:29]
	v_mfma_f32_16x16x32_bf16 v[18:21], v[168:171], v[210:213], v[18:21]
	v_mfma_f32_16x16x32_bf16 v[10:13], v[160:163], v[218:221], v[10:13]
	v_mfma_f32_16x16x32_bf16 v[6:9], v[168:171], v[218:221], v[6:9]
	s_setprio 0
	s_setprio 1
	v_mfma_f32_16x16x32_bf16 v[62:65], v[172:175], v[188:191], v[62:65]
	v_mfma_f32_16x16x32_bf16 v[54:57], v[180:183], v[188:191], v[54:57]
	v_mfma_f32_16x16x32_bf16 v[46:49], v[172:175], v[198:201], v[46:49]
	v_mfma_f32_16x16x32_bf16 v[38:41], v[180:183], v[198:201], v[38:41]
	v_mfma_f32_16x16x32_bf16 v[30:33], v[172:175], v[206:209], v[30:33]
	v_mfma_f32_16x16x32_bf16 v[22:25], v[180:183], v[206:209], v[22:25]
	v_mfma_f32_16x16x32_bf16 v[14:17], v[172:175], v[214:217], v[14:17]
	v_mfma_f32_16x16x32_bf16 v[2:5], v[180:183], v[214:217], v[2:5]
	v_mfma_f32_16x16x32_bf16 v[62:65], v[176:179], v[192:195], v[62:65]
	v_mfma_f32_16x16x32_bf16 v[54:57], v[184:187], v[192:195], v[54:57]
	v_mfma_f32_16x16x32_bf16 v[46:49], v[176:179], v[202:205], v[46:49]
	v_mfma_f32_16x16x32_bf16 v[38:41], v[184:187], v[202:205], v[38:41]
	v_mfma_f32_16x16x32_bf16 v[30:33], v[176:179], v[210:213], v[30:33]
	v_mfma_f32_16x16x32_bf16 v[22:25], v[184:187], v[210:213], v[22:25]
	v_mfma_f32_16x16x32_bf16 v[14:17], v[176:179], v[218:221], v[14:17]
	v_mfma_f32_16x16x32_bf16 v[2:5], v[184:187], v[218:221], v[2:5]
	s_setprio 0
	s_barrier
	s_add_i32 s75, 0, 0x18000
	v_add_u32_e32 v155, s75, v150
	s_add_i32 s76, 0, 0x1c000
	ds_read_b128 v[156:159], v155
	ds_read_b128 v[160:163], v155 offset:1024
	ds_read_b128 v[164:167], v155 offset:2048
	ds_read_b128 v[168:171], v155 offset:3072
	v_add_u32_e32 v155, s76, v150
	ds_read_b128 v[172:175], v155
	ds_read_b128 v[176:179], v155 offset:1024
	ds_read_b128 v[180:183], v155 offset:2048
	ds_read_b128 v[184:187], v155 offset:3072
	s_add_u32 s48, s48, 0x100000
	s_addc_u32 s49, s49, 0
	s_mov_b32 m0, s43
	s_nop 0
	global_load_lds_dwordx4 v[224:225], off
	s_mov_b32 m0, s55
	s_nop 0
	global_load_lds_dwordx4 v[226:227], off
	s_mov_b32 m0, s56
	v_lshl_add_u64 v[228:229], s[48:49], 0, v[136:137]
	ds_read_b128 v[188:191], v154 offset:32768
	ds_read_b128 v[192:195], v154 offset:33792
	ds_read_b128 v[198:201], v154 offset:34816
	ds_read_b128 v[202:205], v154 offset:35840
	ds_read_b128 v[206:209], v154 offset:36864
	ds_read_b128 v[210:213], v154 offset:37888
	ds_read_b128 v[214:217], v154 offset:38912
	ds_read_b128 v[218:221], v154 offset:39936
	global_load_lds_dwordx4 v[228:229], off
	v_lshl_add_u64 v[228:229], s[48:49], 0, v[132:133]
	s_mov_b32 m0, s57
	s_nop 0
	global_load_lds_dwordx4 v[228:229], off
	s_waitcnt vmcnt(8)
	s_waitcnt lgkmcnt(0)
	s_barrier
; #define PG8_STAGE(bufoff, gbase, voff) do { _Pragma("unroll") for (int _i = 0; _i < 2; ++_i) \
;         __builtin_amdgcn_global_load_lds((const unsigned*)((const char*)(gbase) + (voff)[_i]), (PG8_LAS unsigned*)(lds + (bufoff) + ldsw + _i * 8192), 16, 0, 0); } while (0)
; #define PG8_LDA(dst, b, h) do { _Pragma("unroll") for (int m = 0; m < 4; ++m) _Pragma("unroll") for (int k = 0; k < 2; ++k) dst[m][k] = *(const PG8_LAS bf16x8*)(lds + PG8_SA(b, h) + aoff + m * 2048 + k * 1024); } while (0)
; #define PG8_LDB(dst, b, h) do { _Pragma("unroll") for (int n = 0; n < 2; ++n) _Pragma("unroll") for (int k = 0; k < 2; ++k) dst[n][k] = *(const PG8_LAS bf16x8*)(lds + PG8_SB(b, h) + boff + n * 2048 + k * 1024); } while (0)
; #define PG8_MMA(ai, bj, At, Bt) do { __builtin_amdgcn_s_setprio(1); _Pragma("unroll") for (int m = 0; m < 4; ++m) _Pragma("unroll") for (int n = 0; n < 2; ++n) _Pragma("unroll") for (int k = 0; k < 2; ++k) \
;         acc[ai][bj][m][n] = __builtin_amdgcn_mfma_f32_16x16x32_bf16(Bt[n][k], At[m][k], acc[ai][bj][m][n], 0, 0, 0); __builtin_amdgcn_s_setprio(0); } while (0)
; #define PG8_WAIT_V(n) asm volatile("s_waitcnt vmcnt(" #n ")" ::: "memory")
; #define PG8_WAIT_L(n) asm volatile("s_waitcnt lgkmcnt(" #n ")" ::: "memory")
; #define PG8_BAR __builtin_amdgcn_s_barrier()
; #define PG8_SCHED __builtin_amdgcn_sched_barrier(0)
; template <class Epi, class Sched, bool ALIGN_EPI = false, bool SP2 = false>
; __device__ __forceinline__ void gemm_phase(PG8_LAS unsigned char* lds, const Gemm g, const Sched& S, const Epi& E) {
;     ...
;             PG8_LDB(B0, 1, 0); PG8_LDB(B1, 1, 1); PG8_SCHED; PG8_LDA(At, 1, 0); PG8_STAGE(PG8_SA(0, 1), a2 + hstep, voffA);
;             PG8_WAIT_V(8); PG8_WAIT_L(0); PG8_BAR; PG8_MMA(0, 0, At, B0); PG8_MMA(0, 1, At, B1); PG8_BAR; PG8_SCHED;
;             PG8_LDA(At, 1, 1); PG8_STAGE(PG8_SB(1, 0), b3, voffB); PG8_STAGE(PG8_SB(1, 1), b3 + hstep, voffB); PG8_STAGE(PG8_SA(1, 0), a3, voffA);
;             PG8_WAIT_V(8); PG8_WAIT_L(0); PG8_BAR; PG8_MMA(1, 0, At, B0); PG8_MMA(1, 1, At, B1); PG8_BAR; PG8_SCHED;
	s_setprio 1
	s_waitcnt lgkmcnt(0)
	v_mfma_f32_16x16x32_bf16 v[122:125], v[156:159], v[188:191], v[122:125]
	v_mfma_f32_16x16x32_bf16 v[114:117], v[164:167], v[188:191], v[114:117]
	v_mfma_f32_16x16x32_bf16 v[106:109], v[156:159], v[198:201], v[106:109]
	v_mfma_f32_16x16x32_bf16 v[98:101], v[164:167], v[198:201], v[98:101]
	v_mfma_f32_16x16x32_bf16 v[90:93], v[156:159], v[206:209], v[90:93]
	v_mfma_f32_16x16x32_bf16 v[82:85], v[164:167], v[206:209], v[82:85]
	v_mfma_f32_16x16x32_bf16 v[74:77], v[156:159], v[214:217], v[74:77]
	v_mfma_f32_16x16x32_bf16 v[66:69], v[164:167], v[214:217], v[66:69]
	v_mfma_f32_16x16x32_bf16 v[122:125], v[160:163], v[192:195], v[122:125]
	v_mfma_f32_16x16x32_bf16 v[114:117], v[168:171], v[192:195], v[114:117]
	v_mfma_f32_16x16x32_bf16 v[106:109], v[160:163], v[202:205], v[106:109]
	v_mfma_f32_16x16x32_bf16 v[98:101], v[168:171], v[202:205], v[98:101]
	v_mfma_f32_16x16x32_bf16 v[90:93], v[160:163], v[210:213], v[90:93]
	v_mfma_f32_16x16x32_bf16 v[82:85], v[168:171], v[210:213], v[82:85]
	v_mfma_f32_16x16x32_bf16 v[74:77], v[160:163], v[218:221], v[74:77]
	v_mfma_f32_16x16x32_bf16 v[66:69], v[168:171], v[218:221], v[66:69]
	s_setprio 0
	s_setprio 1
	v_mfma_f32_16x16x32_bf16 v[126:129], v[172:175], v[188:191], v[126:129]
	v_mfma_f32_16x16x32_bf16 v[118:121], v[180:183], v[188:191], v[118:121]
	v_mfma_f32_16x16x32_bf16 v[110:113], v[172:175], v[198:201], v[110:113]
	v_mfma_f32_16x16x32_bf16 v[102:105], v[180:183], v[198:201], v[102:105]
	v_mfma_f32_16x16x32_bf16 v[94:97], v[172:175], v[206:209], v[94:97]
	v_mfma_f32_16x16x32_bf16 v[86:89], v[180:183], v[206:209], v[86:89]
	v_mfma_f32_16x16x32_bf16 v[78:81], v[172:175], v[214:217], v[78:81]
	v_mfma_f32_16x16x32_bf16 v[70:73], v[180:183], v[214:217], v[70:73]
	v_mfma_f32_16x16x32_bf16 v[126:129], v[176:179], v[192:195], v[126:129]
	v_mfma_f32_16x16x32_bf16 v[118:121], v[184:187], v[192:195], v[118:121]
	v_mfma_f32_16x16x32_bf16 v[110:113], v[176:179], v[202:205], v[110:113]
	v_mfma_f32_16x16x32_bf16 v[102:105], v[184:187], v[202:205], v[102:105]
	v_mfma_f32_16x16x32_bf16 v[94:97], v[176:179], v[210:213], v[94:97]
	v_mfma_f32_16x16x32_bf16 v[86:89], v[184:187], v[210:213], v[86:89]
	v_mfma_f32_16x16x32_bf16 v[78:81], v[176:179], v[218:221], v[78:81]
	v_mfma_f32_16x16x32_bf16 v[70:73], v[184:187], v[218:221], v[70:73]
	s_setprio 0
	s_barrier
	s_add_i32 s48, s75, s52
	v_lshl_add_u64 v[146:147], v[146:147], 0, s[12:13]
	s_mov_b32 m0, s48
	ds_read_b128 v[188:191], v154 offset:49152
	ds_read_b128 v[192:195], v154 offset:50176
	ds_read_b128 v[198:201], v154 offset:51200
	ds_read_b128 v[202:205], v154 offset:52224
	ds_read_b128 v[206:209], v154 offset:53248
	ds_read_b128 v[210:213], v154 offset:54272
	ds_read_b128 v[214:217], v154 offset:55296
	ds_read_b128 v[218:221], v154 offset:56320
	global_load_lds_dwordx4 v[146:147], off
	s_add_i32 m0, s48, 0x2000
	s_add_u32 s46, s46, 0x100080
	v_lshl_add_u64 v[146:147], v[222:223], 0, s[12:13]
	s_addc_u32 s47, s47, 0
	s_add_i32 s48, s76, s52
	global_load_lds_dwordx4 v[146:147], off
	v_lshl_add_u64 v[146:147], s[46:47], 0, v[134:135]
	s_mov_b32 m0, s48
	s_nop 0
	global_load_lds_dwordx4 v[146:147], off
	v_lshl_add_u64 v[146:147], s[46:47], 0, v[130:131]
	s_add_i32 m0, s48, 0x2000
	s_nop 0
	global_load_lds_dwordx4 v[146:147], off
	s_waitcnt vmcnt(6)
	s_waitcnt lgkmcnt(0)
	s_barrier
	s_setprio 1
	s_waitcnt lgkmcnt(0)
	v_mfma_f32_16x16x32_bf16 v[58:61], v[156:159], v[188:191], v[58:61]
	v_mfma_f32_16x16x32_bf16 v[50:53], v[164:167], v[188:191], v[50:53]
	v_mfma_f32_16x16x32_bf16 v[42:45], v[156:159], v[198:201], v[42:45]
	v_mfma_f32_16x16x32_bf16 v[34:37], v[164:167], v[198:201], v[34:37]
	v_mfma_f32_16x16x32_bf16 v[26:29], v[156:159], v[206:209], v[26:29]
	v_mfma_f32_16x16x32_bf16 v[18:21], v[164:167], v[206:209], v[18:21]
	v_mfma_f32_16x16x32_bf16 v[10:13], v[156:159], v[214:217], v[10:13]
	v_mfma_f32_16x16x32_bf16 v[6:9], v[164:167], v[214:217], v[6:9]
	v_mfma_f32_16x16x32_bf16 v[58:61], v[160:163], v[192:195], v[58:61]
	v_mfma_f32_16x16x32_bf16 v[50:53], v[168:171], v[192:195], v[50:53]
	v_mfma_f32_16x16x32_bf16 v[42:45], v[160:163], v[202:205], v[42:45]
	v_mfma_f32_16x16x32_bf16 v[34:37], v[168:171], v[202:205], v[34:37]
	v_mfma_f32_16x16x32_bf16 v[26:29], v[160:163], v[210:213], v[26:29]
	v_mfma_f32_16x16x32_bf16 v[18:21], v[168:171], v[210:213], v[18:21]
	v_mfma_f32_16x16x32_bf16 v[10:13], v[160:163], v[218:221], v[10:13]
	v_mfma_f32_16x16x32_bf16 v[6:9], v[168:171], v[218:221], v[6:9]
	s_setprio 0
	s_setprio 1
	v_mfma_f32_16x16x32_bf16 v[62:65], v[172:175], v[188:191], v[62:65]
	v_mfma_f32_16x16x32_bf16 v[54:57], v[180:183], v[188:191], v[54:57]
	v_mfma_f32_16x16x32_bf16 v[46:49], v[172:175], v[198:201], v[46:49]
	v_mfma_f32_16x16x32_bf16 v[38:41], v[180:183], v[198:201], v[38:41]
	v_mfma_f32_16x16x32_bf16 v[30:33], v[172:175], v[206:209], v[30:33]
	v_mfma_f32_16x16x32_bf16 v[22:25], v[180:183], v[206:209], v[22:25]
	v_mfma_f32_16x16x32_bf16 v[14:17], v[172:175], v[214:217], v[14:17]
	v_mfma_f32_16x16x32_bf16 v[2:5], v[180:183], v[214:217], v[2:5]
	v_mfma_f32_16x16x32_bf16 v[62:65], v[176:179], v[192:195], v[62:65]
	v_mfma_f32_16x16x32_bf16 v[54:57], v[184:187], v[192:195], v[54:57]
	v_mfma_f32_16x16x32_bf16 v[46:49], v[176:179], v[202:205], v[46:49]
	v_mfma_f32_16x16x32_bf16 v[38:41], v[184:187], v[202:205], v[38:41]
	v_mfma_f32_16x16x32_bf16 v[30:33], v[176:179], v[210:213], v[30:33]
	v_mfma_f32_16x16x32_bf16 v[22:25], v[184:187], v[210:213], v[22:25]
	v_mfma_f32_16x16x32_bf16 v[14:17], v[176:179], v[218:221], v[14:17]
	v_mfma_f32_16x16x32_bf16 v[2:5], v[184:187], v[218:221], v[2:5]
	s_setprio 0
	s_barrier
	s_add_i32 s74, s74, 2
	s_add_u32 s44, s44, 0x100
	s_addc_u32 s45, s45, 0
	s_add_u32 s72, s72, 0x100
	s_addc_u32 s73, s73, 0
	s_cmp_gt_u32 s74, 61
	s_cbranch_scc0 .LBB0_881
	s_and_b64 vcc, exec, s[16:17]
	s_cbranch_vccz .LBB0_884
	s_barrier

; #define PG8_STAGE(bufoff, gbase, voff) do { _Pragma("unroll") for (int _i = 0; _i < 2; ++_i) \
;         __builtin_amdgcn_global_load_lds((const unsigned*)((const char*)(gbase) + (voff)[_i]), (PG8_LAS unsigned*)(lds + (bufoff) + ldsw + _i * 8192), 16, 0, 0); } while (0)
; #define PG8_WAIT_V(n) asm volatile("s_waitcnt vmcnt(" #n ")" ::: "memory")
; #define PG8_BAR __builtin_amdgcn_s_barrier()
; template <class Epi, class Sched, bool ALIGN_EPI = false, bool SP2 = false>
; __device__ __forceinline__ void gemm_phase(PG8_LAS unsigned char* lds, const Gemm g, const Sched& S, const Epi& E) {
;     ...
;     const unsigned ldsw = (unsigned)wid * 1024u;
;     const int aoff = lds_byte(wr * 64 + fr, fq * 8), boff = lds_byte(wc * 32 + fr, fq * 8);
;     ...
;         PG8_STAGE(PG8_SB(1, 0), cB + kstep, voffB); PG8_STAGE(PG8_SA(1, 0), cA + kstep, voffA); PG8_STAGE(PG8_SB(1, 1), cB + hstep + kstep, voffB);
;         PG8_WAIT_V(6); PG8_BAR;
.LBB0_970:
	s_add_u32 s16, s2, 0x27e00000
	s_addc_u32 s17, s3, 0
	s_add_u32 s34, s2, 0x18a00000
	s_mov_b64 s[36:37], 0x80
	s_addc_u32 s35, s3, 0
	s_and_b32 s56, s5, 3
	s_add_i32 m0, s52, 0x18000
	v_lshl_add_u64 v[8:9], v[8:9], 0, s[36:37]
	s_lshl_b32 s5, s4, 13
	s_lshl_b32 s6, s56, 12
	s_waitcnt vmcnt(2)
	s_barrier
	global_load_lds_dwordx4 v[8:9], off
	v_lshl_add_u64 v[6:7], v[6:7], 0, s[36:37]
	s_add_i32 m0, s52, 0x1a000
	s_add_i32 s57, s52, 0x8000
	s_add_i32 s58, s52, 0xa000
	global_load_lds_dwordx4 v[6:7], off
	v_mov_b32_e32 v230, v2
	v_mov_b32_e32 v231, v3
	v_lshl_add_u64 v[2:3], v[2:3], 0, s[36:37]
	s_mov_b32 m0, s57
	s_add_u32 s2, s44, 0x2b0080
	global_load_lds_dwordx4 v[2:3], off
	v_mov_b32_e32 v232, v4
	v_mov_b32_e32 v233, v5
	v_lshl_add_u64 v[2:3], v[4:5], 0, s[36:37]
	s_mov_b32 m0, s58
	s_addc_u32 s3, s45, 0
	global_load_lds_dwordx4 v[2:3], off
	s_add_i32 m0, s52, 0x1c000
	v_lshl_add_u64 v[2:3], s[2:3], 0, v[132:133]
	global_load_lds_dwordx4 v[2:3], off
	v_lshl_add_u64 v[2:3], s[2:3], 0, v[136:137]
	s_add_i32 m0, s52, 0x1e000
	v_lshlrev_b32_e32 v7, 6, v1
	global_load_lds_dwordx4 v[2:3], off
	v_bfe_u32 v2, v1, 4, 2
	v_and_b32_e32 v3, 15, v1
	v_lshlrev_b32_e32 v5, 4, v2
	s_movk_i32 s2, 0x3c0
	v_lshl_or_b32 v150, s4, 6, v3
	v_lshlrev_b32_e32 v4, 3, v2
	v_lshl_or_b32 v3, v3, 6, v5
	v_lshlrev_b32_e32 v6, 2, v1
	v_and_or_b32 v5, v7, s2, v5
	v_cmp_eq_u32_e64 s[2:3], 0, v2
	v_add_u16_e32 v2, v10, v11
	v_and_b32_e32 v6, 32, v6
	s_waitcnt vmcnt(6)
	s_cmpk_lt_u32 s38, 0x100
	v_lshrrev_b16_e32 v2, 1, v2
	v_bitop3_b32 v3, v3, s5, v6 bitop3:0xde
	v_bitop3_b32 v151, s6, v5, v6 bitop3:0xf6
	s_cselect_b64 s[38:39], -1, 0
	v_add_lshl_u32 v138, v12, v2, 1
	v_add_lshl_u32 v140, v13, v2, 1
	s_add_i32 s62, 0, 0x10000
	s_add_i32 s63, 0, 0x14000
	v_mbcnt_lo_u32_b32 v2, -1, 0
	v_lshl_or_b32 v152, s56, 5, v4
	v_or_b32_e32 v153, 16, v150
	v_or_b32_e32 v154, 32, v150
	v_or_b32_e32 v155, 48, v150
	v_add_u32_e32 v156, 0x80, v150
	v_add_u32_e32 v157, 0x90, v150
	v_add_u32_e32 v158, 0xa0, v150
	v_add_u32_e32 v159, 0xb0, v150
	s_ashr_i32 s59, s22, 31
	s_mov_b32 s60, s22
	s_ashr_i32 s61, s14, 31
	v_mov_b32_e32 v139, v133
	v_mov_b32_e32 v141, v133
	v_mov_b64_e32 v[142:143], 0x200
	v_mov_b64_e32 v[144:145], 0x1ff
	v_add_u32_e32 v160, s62, v151
	v_add_u32_e32 v161, s63, v151
	v_add_u32_e32 v162, 0, v3
	v_mbcnt_hi_u32_b32 v163, -1, v2
	s_mov_b32 s66, 0
	s_barrier
	s_branch .LBB0_973

; #define PG8_STAGE(bufoff, gbase, voff) do { _Pragma("unroll") for (int _i = 0; _i < 2; ++_i) \
;         __builtin_amdgcn_global_load_lds((const unsigned*)((const char*)(gbase) + (voff)[_i]), (PG8_LAS unsigned*)(lds + (bufoff) + ldsw + _i * 8192), 16, 0, 0); } while (0)
; #define PG8_LDA(dst, b, h) do { _Pragma("unroll") for (int m = 0; m < 4; ++m) _Pragma("unroll") for (int k = 0; k < 2; ++k) dst[m][k] = *(const PG8_LAS bf16x8*)(lds + PG8_SA(b, h) + aoff + m * 2048 + k * 1024); } while (0)
; #define PG8_LDB(dst, b, h) do { _Pragma("unroll") for (int n = 0; n < 2; ++n) _Pragma("unroll") for (int k = 0; k < 2; ++k) dst[n][k] = *(const PG8_LAS bf16x8*)(lds + PG8_SB(b, h) + boff + n * 2048 + k * 1024); } while (0)
; #define PG8_MMA(ai, bj, At, Bt) do { __builtin_amdgcn_s_setprio(1); _Pragma("unroll") for (int m = 0; m < 4; ++m) _Pragma("unroll") for (int n = 0; n < 2; ++n) _Pragma("unroll") for (int k = 0; k < 2; ++k) \
;         acc[ai][bj][m][n] = __builtin_amdgcn_mfma_f32_16x16x32_bf16(Bt[n][k], At[m][k], acc[ai][bj][m][n], 0, 0, 0); __builtin_amdgcn_s_setprio(0); } while (0)
; #define PG8_WAIT_V(n) asm volatile("s_waitcnt vmcnt(" #n ")" ::: "memory")
; #define PG8_WAIT_L(n) asm volatile("s_waitcnt lgkmcnt(" #n ")" ::: "memory")
; #define PG8_BAR __builtin_amdgcn_s_barrier()
; #define PG8_SCHED __builtin_amdgcn_sched_barrier(0)
; template <class Epi, class Sched, bool ALIGN_EPI = false, bool SP2 = false>
; __device__ __forceinline__ void gemm_phase(PG8_LAS unsigned char* lds, const Gemm g, const Sched& S, const Epi& E) {
;     ...
;             PG8_LDB(B0, 0, 0); PG8_LDB(B1, 0, 1); PG8_SCHED; PG8_LDA(At, 0, 0); PG8_STAGE(PG8_SA(1, 1), a1 + hstep, voffA);
;             PG8_WAIT_V(8); PG8_WAIT_L(0); PG8_BAR; PG8_MMA(0, 0, At, B0); PG8_MMA(0, 1, At, B1); PG8_BAR; PG8_SCHED;
;             PG8_LDA(At, 0, 1); PG8_STAGE(PG8_SB(0, 0), b2, voffB); PG8_STAGE(PG8_SB(0, 1), b2 + hstep, voffB); PG8_STAGE(PG8_SA(0, 0), a2, voffA);
.LBB0_984:
	ds_read_b128 v[146:149], v160
	ds_read_b128 v[164:167], v160 offset:1024
	ds_read_b128 v[168:171], v160 offset:2048
	ds_read_b128 v[172:175], v160 offset:3072
	ds_read_b128 v[176:179], v161
	ds_read_b128 v[180:183], v161 offset:1024
	ds_read_b128 v[184:187], v161 offset:2048
	ds_read_b128 v[188:191], v161 offset:3072
	s_add_u32 s44, s42, 0xffd50080
	s_addc_u32 s45, s43, -1
	s_cmpk_eq_i32 s71, 0xa8
	s_cselect_b32 s47, s7, s45
	s_cselect_b32 s46, s6, s44
	s_cselect_b32 s45, s41, s70
	s_cselect_b32 s44, s40, s69
	v_lshl_add_u64 v[226:227], v[230:231], 0, s[36:37]
	s_mov_b32 m0, s57
	s_nop 0
	global_load_lds_dwordx4 v[226:227], off
	v_lshl_add_u64 v[226:227], v[232:233], 0, s[36:37]
	s_mov_b32 m0, s58
	s_nop 0
	global_load_lds_dwordx4 v[226:227], off
	v_lshl_add_u64 v[226:227], s[42:43], 0, v[138:139]
	s_add_i32 m0, s52, 0xc000
	ds_read_b128 v[192:195], v162
	ds_read_b128 v[198:201], v162 offset:1024
	ds_read_b128 v[202:205], v162 offset:2048
	ds_read_b128 v[206:209], v162 offset:3072
	ds_read_b128 v[210:213], v162 offset:4096
	ds_read_b128 v[214:217], v162 offset:5120
	ds_read_b128 v[218:221], v162 offset:6144
	ds_read_b128 v[222:225], v162 offset:7168
	global_load_lds_dwordx4 v[226:227], off
	v_lshl_add_u64 v[226:227], s[42:43], 0, v[140:141]
	s_add_i32 m0, s52, 0xe000
	s_nop 0
	global_load_lds_dwordx4 v[226:227], off
	s_waitcnt vmcnt(8)
	s_waitcnt lgkmcnt(0)
	s_barrier
	s_setprio 1
	s_waitcnt lgkmcnt(0)
	v_mfma_f32_16x16x32_bf16 v[126:129], v[146:149], v[192:195], v[126:129]
	v_mfma_f32_16x16x32_bf16 v[122:125], v[168:171], v[192:195], v[122:125]
	v_mfma_f32_16x16x32_bf16 v[110:113], v[146:149], v[202:205], v[110:113]
	v_mfma_f32_16x16x32_bf16 v[106:109], v[168:171], v[202:205], v[106:109]
	v_mfma_f32_16x16x32_bf16 v[94:97], v[146:149], v[210:213], v[94:97]
	v_mfma_f32_16x16x32_bf16 v[90:93], v[168:171], v[210:213], v[90:93]
	v_mfma_f32_16x16x32_bf16 v[78:81], v[146:149], v[218:221], v[78:81]
	v_mfma_f32_16x16x32_bf16 v[74:77], v[168:171], v[218:221], v[74:77]
	v_mfma_f32_16x16x32_bf16 v[126:129], v[164:167], v[198:201], v[126:129]
	v_mfma_f32_16x16x32_bf16 v[122:125], v[172:175], v[198:201], v[122:125]
	v_mfma_f32_16x16x32_bf16 v[110:113], v[164:167], v[206:209], v[110:113]
	v_mfma_f32_16x16x32_bf16 v[106:109], v[172:175], v[206:209], v[106:109]
	v_mfma_f32_16x16x32_bf16 v[94:97], v[164:167], v[214:217], v[94:97]
	v_mfma_f32_16x16x32_bf16 v[90:93], v[172:175], v[214:217], v[90:93]
	v_mfma_f32_16x16x32_bf16 v[78:81], v[164:167], v[222:225], v[78:81]
	v_mfma_f32_16x16x32_bf16 v[74:77], v[172:175], v[222:225], v[74:77]
	s_setprio 0
	s_setprio 1
	v_mfma_f32_16x16x32_bf16 v[118:121], v[176:179], v[192:195], v[118:121]
	v_mfma_f32_16x16x32_bf16 v[114:117], v[184:187], v[192:195], v[114:117]
	v_mfma_f32_16x16x32_bf16 v[102:105], v[176:179], v[202:205], v[102:105]
	v_mfma_f32_16x16x32_bf16 v[98:101], v[184:187], v[202:205], v[98:101]
	v_mfma_f32_16x16x32_bf16 v[86:89], v[176:179], v[210:213], v[86:89]
	v_mfma_f32_16x16x32_bf16 v[82:85], v[184:187], v[210:213], v[82:85]
	v_mfma_f32_16x16x32_bf16 v[70:73], v[176:179], v[218:221], v[70:73]
	v_mfma_f32_16x16x32_bf16 v[66:69], v[184:187], v[218:221], v[66:69]
	v_mfma_f32_16x16x32_bf16 v[118:121], v[180:183], v[198:201], v[118:121]
	v_mfma_f32_16x16x32_bf16 v[114:117], v[188:191], v[198:201], v[114:117]
	v_mfma_f32_16x16x32_bf16 v[102:105], v[180:183], v[206:209], v[102:105]
	v_mfma_f32_16x16x32_bf16 v[98:101], v[188:191], v[206:209], v[98:101]
	v_mfma_f32_16x16x32_bf16 v[86:89], v[180:183], v[214:217], v[86:89]
	v_mfma_f32_16x16x32_bf16 v[82:85], v[188:191], v[214:217], v[82:85]
	v_mfma_f32_16x16x32_bf16 v[70:73], v[180:183], v[222:225], v[70:73]
	v_mfma_f32_16x16x32_bf16 v[66:69], v[188:191], v[222:225], v[66:69]
	s_setprio 0
	s_barrier
	s_add_i32 s72, s62, s51
	v_lshl_add_u64 v[226:227], s[44:45], 0, v[132:133]
	s_mov_b32 m0, s72
	ds_read_b128 v[192:195], v162 offset:16384
	ds_read_b128 v[198:201], v162 offset:17408
	ds_read_b128 v[202:205], v162 offset:18432
	ds_read_b128 v[206:209], v162 offset:19456
	ds_read_b128 v[210:213], v162 offset:20480
	ds_read_b128 v[214:217], v162 offset:21504
	ds_read_b128 v[218:221], v162 offset:22528
	ds_read_b128 v[222:225], v162 offset:23552
	global_load_lds_dwordx4 v[226:227], off
	s_add_i32 m0, s72, 0x2000
	s_add_u32 s72, s44, 0x2b0000
	v_lshl_add_u64 v[228:229], s[44:45], 0, v[136:137]
	s_addc_u32 s73, s45, 0
	s_add_i32 s74, s63, s51
	global_load_lds_dwordx4 v[228:229], off
	v_lshl_add_u64 v[230:231], s[72:73], 0, v[132:133]
	s_mov_b32 m0, s74
	v_lshl_add_u64 v[232:233], s[46:47], 0, v[134:135]
	global_load_lds_dwordx4 v[230:231], off
	v_lshl_add_u64 v[230:231], s[72:73], 0, v[136:137]
	s_add_i32 m0, s74, 0x2000
	s_nop 0
	global_load_lds_dwordx4 v[230:231], off
	v_lshl_add_u64 v[230:231], s[46:47], 0, v[130:131]
	s_waitcnt vmcnt(6)
	s_waitcnt lgkmcnt(0)
	s_barrier
; #define PG8_STAGE(bufoff, gbase, voff) do { _Pragma("unroll") for (int _i = 0; _i < 2; ++_i) \
;         __builtin_amdgcn_global_load_lds((const unsigned*)((const char*)(gbase) + (voff)[_i]), (PG8_LAS unsigned*)(lds + (bufoff) + ldsw + _i * 8192), 16, 0, 0); } while (0)
; #define PG8_LDA(dst, b, h) do { _Pragma("unroll") for (int m = 0; m < 4; ++m) _Pragma("unroll") for (int k = 0; k < 2; ++k) dst[m][k] = *(const PG8_LAS bf16x8*)(lds + PG8_SA(b, h) + aoff + m * 2048 + k * 1024); } while (0)
; #define PG8_LDB(dst, b, h) do { _Pragma("unroll") for (int n = 0; n < 2; ++n) _Pragma("unroll") for (int k = 0; k < 2; ++k) dst[n][k] = *(const PG8_LAS bf16x8*)(lds + PG8_SB(b, h) + boff + n * 2048 + k * 1024); } while (0)
; #define PG8_MMA(ai, bj, At, Bt) do { __builtin_amdgcn_s_setprio(1); _Pragma("unroll") for (int m = 0; m < 4; ++m) _Pragma("unroll") for (int n = 0; n < 2; ++n) _Pragma("unroll") for (int k = 0; k < 2; ++k) \
;         acc[ai][bj][m][n] = __builtin_amdgcn_mfma_f32_16x16x32_bf16(Bt[n][k], At[m][k], acc[ai][bj][m][n], 0, 0, 0); __builtin_amdgcn_s_setprio(0); } while (0)
; #define PG8_WAIT_V(n) asm volatile("s_waitcnt vmcnt(" #n ")" ::: "memory")
; #define PG8_WAIT_L(n) asm volatile("s_waitcnt lgkmcnt(" #n ")" ::: "memory")
; #define PG8_BAR __builtin_amdgcn_s_barrier()
; #define PG8_SCHED __builtin_amdgcn_sched_barrier(0)
; template <class Epi, class Sched, bool ALIGN_EPI = false, bool SP2 = false>
; __device__ __forceinline__ void gemm_phase(PG8_LAS unsigned char* lds, const Gemm g, const Sched& S, const Epi& E) {
;     ...
;             PG8_LDA(At, 0, 1); PG8_STAGE(PG8_SB(0, 0), b2, voffB); PG8_STAGE(PG8_SB(0, 1), b2 + hstep, voffB); PG8_STAGE(PG8_SA(0, 0), a2, voffA);
;             PG8_WAIT_V(8); PG8_WAIT_L(0); PG8_BAR; PG8_MMA(1, 0, At, B0); PG8_MMA(1, 1, At, B1); PG8_BAR; PG8_SCHED;
;             PG8_LDB(B0, 1, 0); PG8_LDB(B1, 1, 1); PG8_SCHED; PG8_LDA(At, 1, 0); PG8_STAGE(PG8_SA(0, 1), a2 + hstep, voffA);
	s_setprio 1
	s_waitcnt lgkmcnt(0)
	v_mfma_f32_16x16x32_bf16 v[62:65], v[146:149], v[192:195], v[62:65]
	v_mfma_f32_16x16x32_bf16 v[58:61], v[168:171], v[192:195], v[58:61]
	v_mfma_f32_16x16x32_bf16 v[46:49], v[146:149], v[202:205], v[46:49]
	v_mfma_f32_16x16x32_bf16 v[42:45], v[168:171], v[202:205], v[42:45]
	v_mfma_f32_16x16x32_bf16 v[30:33], v[146:149], v[210:213], v[30:33]
	v_mfma_f32_16x16x32_bf16 v[26:29], v[168:171], v[210:213], v[26:29]
	v_mfma_f32_16x16x32_bf16 v[14:17], v[146:149], v[218:221], v[14:17]
	v_mfma_f32_16x16x32_bf16 v[10:13], v[168:171], v[218:221], v[10:13]
	v_mfma_f32_16x16x32_bf16 v[62:65], v[164:167], v[198:201], v[62:65]
	v_mfma_f32_16x16x32_bf16 v[58:61], v[172:175], v[198:201], v[58:61]
	v_mfma_f32_16x16x32_bf16 v[46:49], v[164:167], v[206:209], v[46:49]
	v_mfma_f32_16x16x32_bf16 v[42:45], v[172:175], v[206:209], v[42:45]
	v_mfma_f32_16x16x32_bf16 v[30:33], v[164:167], v[214:217], v[30:33]
	v_mfma_f32_16x16x32_bf16 v[26:29], v[172:175], v[214:217], v[26:29]
	v_mfma_f32_16x16x32_bf16 v[14:17], v[164:167], v[222:225], v[14:17]
	v_mfma_f32_16x16x32_bf16 v[10:13], v[172:175], v[222:225], v[10:13]
	s_setprio 0
	s_setprio 1
	v_mfma_f32_16x16x32_bf16 v[54:57], v[176:179], v[192:195], v[54:57]
	v_mfma_f32_16x16x32_bf16 v[50:53], v[184:187], v[192:195], v[50:53]
	v_mfma_f32_16x16x32_bf16 v[38:41], v[176:179], v[202:205], v[38:41]
	v_mfma_f32_16x16x32_bf16 v[34:37], v[184:187], v[202:205], v[34:37]
	v_mfma_f32_16x16x32_bf16 v[22:25], v[176:179], v[210:213], v[22:25]
	v_mfma_f32_16x16x32_bf16 v[18:21], v[184:187], v[210:213], v[18:21]
	v_mfma_f32_16x16x32_bf16 v[6:9], v[176:179], v[218:221], v[6:9]
	v_mfma_f32_16x16x32_bf16 v[2:5], v[184:187], v[218:221], v[2:5]
	v_mfma_f32_16x16x32_bf16 v[54:57], v[180:183], v[198:201], v[54:57]
	v_mfma_f32_16x16x32_bf16 v[50:53], v[188:191], v[198:201], v[50:53]
	v_mfma_f32_16x16x32_bf16 v[38:41], v[180:183], v[206:209], v[38:41]
	v_mfma_f32_16x16x32_bf16 v[34:37], v[188:191], v[206:209], v[34:37]
	v_mfma_f32_16x16x32_bf16 v[22:25], v[180:183], v[214:217], v[22:25]
	v_mfma_f32_16x16x32_bf16 v[18:21], v[188:191], v[214:217], v[18:21]
	v_mfma_f32_16x16x32_bf16 v[6:9], v[180:183], v[222:225], v[6:9]
	v_mfma_f32_16x16x32_bf16 v[2:5], v[188:191], v[222:225], v[2:5]
	s_setprio 0
	s_barrier
	s_add_i32 s72, 0, 0x18000
	s_add_i32 s73, 0, 0x1c000
	v_add_u32_e32 v172, s72, v151
	v_add_u32_e32 v188, s73, v151
	ds_read_b128 v[146:149], v172
	ds_read_b128 v[164:167], v172 offset:1024
	ds_read_b128 v[168:171], v172 offset:2048
	ds_read_b128 v[172:175], v172 offset:3072
	ds_read_b128 v[176:179], v188
	ds_read_b128 v[180:183], v188 offset:1024
	ds_read_b128 v[184:187], v188 offset:2048
	ds_read_b128 v[188:191], v188 offset:3072
	s_add_u32 s46, s46, 0x2b0000
	s_addc_u32 s47, s47, 0
	s_mov_b32 m0, s52
	s_nop 0
	global_load_lds_dwordx4 v[230:231], off
	s_mov_b32 m0, s53
	s_nop 0
	global_load_lds_dwordx4 v[232:233], off
	s_mov_b32 m0, s54
	v_lshl_add_u64 v[234:235], s[46:47], 0, v[130:131]
	ds_read_b128 v[192:195], v162 offset:32768
	ds_read_b128 v[198:201], v162 offset:33792
	ds_read_b128 v[202:205], v162 offset:34816
	ds_read_b128 v[206:209], v162 offset:35840
	ds_read_b128 v[210:213], v162 offset:36864
	ds_read_b128 v[214:217], v162 offset:37888
	ds_read_b128 v[218:221], v162 offset:38912
	ds_read_b128 v[222:225], v162 offset:39936
	global_load_lds_dwordx4 v[234:235], off
	v_lshl_add_u64 v[234:235], s[46:47], 0, v[134:135]
	s_mov_b32 m0, s55
	s_nop 0
	global_load_lds_dwordx4 v[234:235], off
	s_waitcnt vmcnt(8)
	s_waitcnt lgkmcnt(0)
	s_barrier
; #define PG8_STAGE(bufoff, gbase, voff) do { _Pragma("unroll") for (int _i = 0; _i < 2; ++_i) \
;         __builtin_amdgcn_global_load_lds((const unsigned*)((const char*)(gbase) + (voff)[_i]), (PG8_LAS unsigned*)(lds + (bufoff) + ldsw + _i * 8192), 16, 0, 0); } while (0)
; #define PG8_LDA(dst, b, h) do { _Pragma("unroll") for (int m = 0; m < 4; ++m) _Pragma("unroll") for (int k = 0; k < 2; ++k) dst[m][k] = *(const PG8_LAS bf16x8*)(lds + PG8_SA(b, h) + aoff + m * 2048 + k * 1024); } while (0)
; #define PG8_LDB(dst, b, h) do { _Pragma("unroll") for (int n = 0; n < 2; ++n) _Pragma("unroll") for (int k = 0; k < 2; ++k) dst[n][k] = *(const PG8_LAS bf16x8*)(lds + PG8_SB(b, h) + boff + n * 2048 + k * 1024); } while (0)
; #define PG8_MMA(ai, bj, At, Bt) do { __builtin_amdgcn_s_setprio(1); _Pragma("unroll") for (int m = 0; m < 4; ++m) _Pragma("unroll") for (int n = 0; n < 2; ++n) _Pragma("unroll") for (int k = 0; k < 2; ++k) \
;         acc[ai][bj][m][n] = __builtin_amdgcn_mfma_f32_16x16x32_bf16(Bt[n][k], At[m][k], acc[ai][bj][m][n], 0, 0, 0); __builtin_amdgcn_s_setprio(0); } while (0)
; #define PG8_WAIT_V(n) asm volatile("s_waitcnt vmcnt(" #n ")" ::: "memory")
; #define PG8_WAIT_L(n) asm volatile("s_waitcnt lgkmcnt(" #n ")" ::: "memory")
; #define PG8_BAR __builtin_amdgcn_s_barrier()
; #define PG8_SCHED __builtin_amdgcn_sched_barrier(0)
; template <class Epi, class Sched, bool ALIGN_EPI = false, bool SP2 = false>
; __device__ __forceinline__ void gemm_phase(PG8_LAS unsigned char* lds, const Gemm g, const Sched& S, const Epi& E) {
;     ...
;             PG8_LDB(B0, 1, 0); PG8_LDB(B1, 1, 1); PG8_SCHED; PG8_LDA(At, 1, 0); PG8_STAGE(PG8_SA(0, 1), a2 + hstep, voffA);
;             PG8_WAIT_V(8); PG8_WAIT_L(0); PG8_BAR; PG8_MMA(0, 0, At, B0); PG8_MMA(0, 1, At, B1); PG8_BAR; PG8_SCHED;
;             PG8_LDA(At, 1, 1); PG8_STAGE(PG8_SB(1, 0), b3, voffB); PG8_STAGE(PG8_SB(1, 1), b3 + hstep, voffB); PG8_STAGE(PG8_SA(1, 0), a3, voffA);
;             PG8_WAIT_V(8); PG8_WAIT_L(0); PG8_BAR; PG8_MMA(1, 0, At, B0); PG8_MMA(1, 1, At, B1); PG8_BAR; PG8_SCHED;
	s_setprio 1
	s_waitcnt lgkmcnt(0)
	v_mfma_f32_16x16x32_bf16 v[126:129], v[146:149], v[192:195], v[126:129]
	v_mfma_f32_16x16x32_bf16 v[122:125], v[168:171], v[192:195], v[122:125]
	v_mfma_f32_16x16x32_bf16 v[110:113], v[146:149], v[202:205], v[110:113]
	v_mfma_f32_16x16x32_bf16 v[106:109], v[168:171], v[202:205], v[106:109]
	v_mfma_f32_16x16x32_bf16 v[94:97], v[146:149], v[210:213], v[94:97]
	v_mfma_f32_16x16x32_bf16 v[90:93], v[168:171], v[210:213], v[90:93]
	v_mfma_f32_16x16x32_bf16 v[78:81], v[146:149], v[218:221], v[78:81]
	v_mfma_f32_16x16x32_bf16 v[74:77], v[168:171], v[218:221], v[74:77]
	v_mfma_f32_16x16x32_bf16 v[126:129], v[164:167], v[198:201], v[126:129]
	v_mfma_f32_16x16x32_bf16 v[122:125], v[172:175], v[198:201], v[122:125]
	v_mfma_f32_16x16x32_bf16 v[110:113], v[164:167], v[206:209], v[110:113]
	v_mfma_f32_16x16x32_bf16 v[106:109], v[172:175], v[206:209], v[106:109]
	v_mfma_f32_16x16x32_bf16 v[94:97], v[164:167], v[214:217], v[94:97]
	v_mfma_f32_16x16x32_bf16 v[90:93], v[172:175], v[214:217], v[90:93]
	v_mfma_f32_16x16x32_bf16 v[78:81], v[164:167], v[222:225], v[78:81]
	v_mfma_f32_16x16x32_bf16 v[74:77], v[172:175], v[222:225], v[74:77]
	s_setprio 0
	s_setprio 1
	v_mfma_f32_16x16x32_bf16 v[118:121], v[176:179], v[192:195], v[118:121]
	v_mfma_f32_16x16x32_bf16 v[114:117], v[184:187], v[192:195], v[114:117]
	v_mfma_f32_16x16x32_bf16 v[102:105], v[176:179], v[202:205], v[102:105]
	v_mfma_f32_16x16x32_bf16 v[98:101], v[184:187], v[202:205], v[98:101]
	v_mfma_f32_16x16x32_bf16 v[86:89], v[176:179], v[210:213], v[86:89]
	v_mfma_f32_16x16x32_bf16 v[82:85], v[184:187], v[210:213], v[82:85]
	v_mfma_f32_16x16x32_bf16 v[70:73], v[176:179], v[218:221], v[70:73]
	v_mfma_f32_16x16x32_bf16 v[66:69], v[184:187], v[218:221], v[66:69]
	v_mfma_f32_16x16x32_bf16 v[118:121], v[180:183], v[198:201], v[118:121]
	v_mfma_f32_16x16x32_bf16 v[114:117], v[188:191], v[198:201], v[114:117]
	v_mfma_f32_16x16x32_bf16 v[102:105], v[180:183], v[206:209], v[102:105]
	v_mfma_f32_16x16x32_bf16 v[98:101], v[188:191], v[206:209], v[98:101]
	v_mfma_f32_16x16x32_bf16 v[86:89], v[180:183], v[214:217], v[86:89]
	v_mfma_f32_16x16x32_bf16 v[82:85], v[188:191], v[214:217], v[82:85]
	v_mfma_f32_16x16x32_bf16 v[70:73], v[180:183], v[222:225], v[70:73]
	v_mfma_f32_16x16x32_bf16 v[66:69], v[188:191], v[222:225], v[66:69]
	s_setprio 0
	s_barrier
	s_add_i32 s46, s72, s51
	v_lshl_add_u64 v[226:227], v[226:227], 0, s[36:37]
	s_mov_b32 m0, s46
	ds_read_b128 v[192:195], v162 offset:49152
	ds_read_b128 v[198:201], v162 offset:50176
	ds_read_b128 v[202:205], v162 offset:51200
	ds_read_b128 v[206:209], v162 offset:52224
	ds_read_b128 v[210:213], v162 offset:53248
	ds_read_b128 v[214:217], v162 offset:54272
	ds_read_b128 v[218:221], v162 offset:55296
	ds_read_b128 v[222:225], v162 offset:56320
	global_load_lds_dwordx4 v[226:227], off
	s_add_i32 m0, s46, 0x2000
	s_add_u32 s44, s44, 0x2b0080
	v_lshl_add_u64 v[226:227], v[228:229], 0, s[36:37]
	s_addc_u32 s45, s45, 0
	s_add_i32 s46, s73, s51
	global_load_lds_dwordx4 v[226:227], off
	v_lshl_add_u64 v[226:227], s[44:45], 0, v[132:133]
	s_mov_b32 m0, s46
	s_nop 0
	global_load_lds_dwordx4 v[226:227], off
	v_lshl_add_u64 v[226:227], s[44:45], 0, v[136:137]
	s_add_i32 m0, s46, 0x2000
	s_nop 0
	global_load_lds_dwordx4 v[226:227], off
	s_waitcnt vmcnt(6)
	s_waitcnt lgkmcnt(0)
	s_barrier
	s_setprio 1
	s_waitcnt lgkmcnt(0)
	v_mfma_f32_16x16x32_bf16 v[62:65], v[146:149], v[192:195], v[62:65]
	v_mfma_f32_16x16x32_bf16 v[58:61], v[168:171], v[192:195], v[58:61]
	v_mfma_f32_16x16x32_bf16 v[46:49], v[146:149], v[202:205], v[46:49]
	v_mfma_f32_16x16x32_bf16 v[42:45], v[168:171], v[202:205], v[42:45]
	v_mfma_f32_16x16x32_bf16 v[30:33], v[146:149], v[210:213], v[30:33]
	v_mfma_f32_16x16x32_bf16 v[26:29], v[168:171], v[210:213], v[26:29]
	v_mfma_f32_16x16x32_bf16 v[14:17], v[146:149], v[218:221], v[14:17]
	v_mfma_f32_16x16x32_bf16 v[10:13], v[168:171], v[218:221], v[10:13]
	v_mfma_f32_16x16x32_bf16 v[62:65], v[164:167], v[198:201], v[62:65]
	v_mfma_f32_16x16x32_bf16 v[58:61], v[172:175], v[198:201], v[58:61]
	v_mfma_f32_16x16x32_bf16 v[46:49], v[164:167], v[206:209], v[46:49]
	v_mfma_f32_16x16x32_bf16 v[42:45], v[172:175], v[206:209], v[42:45]
	v_mfma_f32_16x16x32_bf16 v[30:33], v[164:167], v[214:217], v[30:33]
	v_mfma_f32_16x16x32_bf16 v[26:29], v[172:175], v[214:217], v[26:29]
	v_mfma_f32_16x16x32_bf16 v[14:17], v[164:167], v[222:225], v[14:17]
	v_mfma_f32_16x16x32_bf16 v[10:13], v[172:175], v[222:225], v[10:13]
	s_setprio 0
	s_setprio 1
	v_mfma_f32_16x16x32_bf16 v[54:57], v[176:179], v[192:195], v[54:57]
	v_mfma_f32_16x16x32_bf16 v[50:53], v[184:187], v[192:195], v[50:53]
	v_mfma_f32_16x16x32_bf16 v[38:41], v[176:179], v[202:205], v[38:41]
	v_mfma_f32_16x16x32_bf16 v[34:37], v[184:187], v[202:205], v[34:37]
	v_mfma_f32_16x16x32_bf16 v[22:25], v[176:179], v[210:213], v[22:25]
	v_mfma_f32_16x16x32_bf16 v[18:21], v[184:187], v[210:213], v[18:21]
	v_mfma_f32_16x16x32_bf16 v[6:9], v[176:179], v[218:221], v[6:9]
	v_mfma_f32_16x16x32_bf16 v[2:5], v[184:187], v[218:221], v[2:5]
	v_mfma_f32_16x16x32_bf16 v[54:57], v[180:183], v[198:201], v[54:57]
	v_mfma_f32_16x16x32_bf16 v[50:53], v[188:191], v[198:201], v[50:53]
	v_mfma_f32_16x16x32_bf16 v[38:41], v[180:183], v[206:209], v[38:41]
	v_mfma_f32_16x16x32_bf16 v[34:37], v[188:191], v[206:209], v[34:37]
	v_mfma_f32_16x16x32_bf16 v[22:25], v[180:183], v[214:217], v[22:25]
	v_mfma_f32_16x16x32_bf16 v[18:21], v[188:191], v[214:217], v[18:21]
	v_mfma_f32_16x16x32_bf16 v[6:9], v[180:183], v[222:225], v[6:9]
	v_mfma_f32_16x16x32_bf16 v[2:5], v[188:191], v[222:225], v[2:5]
	s_setprio 0
	s_barrier
	s_add_i32 s71, s71, 2
	s_add_u32 s42, s42, 0x100
	s_addc_u32 s43, s43, 0
	s_add_u32 s69, s69, 0x100
	s_addc_u32 s70, s70, 0
	s_cmpk_gt_u32 s71, 0xa9
	s_cbranch_scc0 .LBB0_984
	s_and_b64 vcc, exec, s[38:39]
	s_cbranch_vccz .LBB0_987
	s_barrier
